# v054 + counted waits at unit boundaries in 8 GEMM phases (F1 F2 F3a F3b F6 F7 F8 F9b): first two segment waits of a unit's first K-loop iteration are vmcnt(8 + unconditional epilogue ops) so the previ
# baseline (speedup 1.0000x reference)
.LBB0_421:
	s_mov_b32 s101, 0
	s_add_u32 s10, s6, 0x63000000
	s_addc_u32 s11, s7, 0
	s_add_u32 s12, s6, 0x44000000
	s_addc_u32 s13, s7, 0
	s_lshl_b64 s[14:15], s[54:55], 3
	s_add_u32 s14, s6, s14
	s_addc_u32 s15, s7, s15
	s_add_u32 s14, s14, 0x100000
	s_addc_u32 s15, s15, 0
	v_bfe_u32 v14, v6, 4, 2
	s_add_u32 s16, s6, 2.0
	v_and_b32_e32 v13, 15, v6
	v_lshlrev_b32_e32 v15, 4, v14
	v_lshlrev_b32_e32 v6, 2, v6
	s_addc_u32 s17, s7, 0
	v_lshl_or_b32 v196, s4, 6, v13
	v_lshl_or_b32 v13, v13, 6, v15
	s_lshl_b32 s4, s4, 13
	v_and_b32_e32 v6, 32, v6
	v_bitop3_b32 v15, v13, s4, v6 bitop3:0xde
	s_lshl_b32 s4, s5, 5
	s_and_b32 s6, s4, 0x60
	s_add_i32 m0, s63, 0x18000
	v_lshl_add_u64 v[2:3], v[2:3], 0, s[44:45]
	s_lshl_b32 s4, s6, 7
	s_waitcnt vmcnt(2)
	s_barrier
	global_load_lds_dwordx4 v[2:3], off
	s_add_i32 m0, s63, 0x1a000
	v_bitop3_b32 v197, v13, s4, v6 bitop3:0xde
	s_add_u32 s4, s24, 0x8000
	v_mov_b32_e32 v159, v163
	v_lshl_add_u64 v[2:3], v[4:5], 0, s[44:45]
	s_addc_u32 s5, s25, 0
	s_add_i32 s67, s63, 0x8000
	v_mov_b32_e32 v161, v163
	global_load_lds_dwordx4 v[2:3], off
	v_lshl_add_u64 v[2:3], s[4:5], 0, v[158:159]
	s_mov_b32 m0, s67
	s_add_i32 s68, s63, 0xa000
	global_load_lds_dwordx4 v[2:3], off
	v_lshl_add_u64 v[2:3], s[4:5], 0, v[160:161]
	s_add_u32 s4, s26, 0x160080
	s_mov_b32 m0, s68
	s_addc_u32 s5, s27, 0
	global_load_lds_dwordx4 v[2:3], off
	s_add_i32 m0, s63, 0x1c000
	v_lshl_add_u64 v[2:3], s[4:5], 0, v[162:163]
	global_load_lds_dwordx4 v[2:3], off
	v_lshl_add_u64 v[2:3], s[4:5], 0, v[172:173]
	s_add_i32 m0, s63, 0x1e000
	s_and_b32 s70, s2, 7
	global_load_lds_dwordx4 v[2:3], off
	v_lshlrev_b32_e32 v2, 10, v10
	v_and_b32_e32 v2, 0xfffff800, v2
	v_lshl_add_u32 v2, v11, 7, v2
	v_and_b32_e32 v3, 1, v10
	v_lshl_or_b32 v2, v3, 6, v2
	v_lshl_add_u32 v174, v12, 1, v2
	v_lshlrev_b32_e32 v2, 10, v7
	s_lshl_b32 s4, s70, 3
	s_ashr_i32 s71, s2, 6
	s_bfe_u32 s73, s2, 0x30003
	v_and_b32_e32 v2, 0xfffff800, v2
	s_waitcnt vmcnt(6)
	s_ashr_i32 s69, s2, 31
	s_add_i32 s72, s4, s71
	s_or_b32 s74, s4, s73
	v_lshl_add_u32 v2, v8, 7, v2
	v_and_b32_e32 v3, 1, v7
	s_cmpk_lt_u32 s18, 0x100
	v_lshl_or_b32 v2, v3, 6, v2
	s_cselect_b64 s[18:19], -1, 0
	s_mov_b32 s75, 0
	v_cmp_eq_u32_e64 s[4:5], 0, v14
	v_lshl_or_b32 v198, v14, 3, s6
	v_mov_b32_e32 v175, v163
	v_lshl_add_u32 v176, v9, 1, v2
	v_mov_b32_e32 v177, v163
	v_add_u32_e32 v199, 0, v15
	s_barrier
	s_branch .LBB0_424

.LBB0_437:
	s_add_u32 s26, s24, 0x4000
	s_addc_u32 s27, s25, 0
	s_cmpk_eq_i32 s82, 0x54
	s_cselect_b32 s58, s20, s26
	s_cselect_b32 s59, s21, s27
	s_cselect_b32 s56, s22, s80
	s_cselect_b32 s57, s23, s81
	s_add_u32 s26, s58, 0x8000
	s_addc_u32 s27, s59, 0
	s_add_i32 s36, 0, 0x10000
	s_add_i32 s38, 0, 0x14000
	v_add_u32_e32 v126, s36, v197
	v_add_u32_e32 v168, s38, v197
	ds_read_b128 v[114:117], v126
	ds_read_b128 v[118:121], v126 offset:1024
	ds_read_b128 v[122:125], v126 offset:2048
	ds_read_b128 v[126:129], v126 offset:3072
	ds_read_b128 v[138:141], v168
	ds_read_b128 v[142:145], v168 offset:1024
	ds_read_b128 v[154:157], v168 offset:2048
	ds_read_b128 v[178:181], v168 offset:3072
	v_lshl_add_u64 v[194:195], s[24:25], 0, v[176:177]
	s_add_i32 m0, s63, 0xc000
	ds_read_b128 v[182:185], v199
	ds_read_b128 v[186:189], v199 offset:1024
	ds_read_b128 v[190:193], v199 offset:2048
	ds_read_b128 v[200:203], v199 offset:3072
	ds_read_b128 v[204:207], v199 offset:4096
	ds_read_b128 v[208:211], v199 offset:5120
	ds_read_b128 v[212:215], v199 offset:6144
	ds_read_b128 v[222:225], v199 offset:7168
	global_load_lds_dwordx4 v[194:195], off
	v_lshl_add_u64 v[194:195], s[24:25], 0, v[174:175]
	s_add_i32 m0, s63, 0xe000
	s_nop 0
	global_load_lds_dwordx4 v[194:195], off
	s_waitcnt vmcnt(56)
	s_cmp_eq_i32 s82, -2
	s_cselect_b32 s100, s101, 0
	s_cmp_lg_u32 s100, 0
	s_cbranch_scc1 .Lrw_skip437_0
	s_waitcnt vmcnt(8)
.Lrw_skip437_0:
	s_waitcnt lgkmcnt(0)
	s_barrier
	v_mfma_f32_16x16x32_bf16 v[150:153], v[114:117], v[182:185], v[150:153]
	v_mfma_f32_16x16x32_bf16 v[146:149], v[122:125], v[182:185], v[146:149]
	v_mfma_f32_16x16x32_bf16 v[110:113], v[114:117], v[190:193], v[110:113]
	v_mfma_f32_16x16x32_bf16 v[106:109], v[122:125], v[190:193], v[106:109]
	v_mfma_f32_16x16x32_bf16 v[94:97], v[114:117], v[204:207], v[94:97]
	v_mfma_f32_16x16x32_bf16 v[90:93], v[122:125], v[204:207], v[90:93]
	v_mfma_f32_16x16x32_bf16 v[78:81], v[114:117], v[212:215], v[78:81]
	v_mfma_f32_16x16x32_bf16 v[74:77], v[122:125], v[212:215], v[74:77]
	v_mfma_f32_16x16x32_bf16 v[150:153], v[118:121], v[186:189], v[150:153]
	v_mfma_f32_16x16x32_bf16 v[146:149], v[126:129], v[186:189], v[146:149]
	v_mfma_f32_16x16x32_bf16 v[110:113], v[118:121], v[200:203], v[110:113]
	v_mfma_f32_16x16x32_bf16 v[106:109], v[126:129], v[200:203], v[106:109]
	v_mfma_f32_16x16x32_bf16 v[94:97], v[118:121], v[208:211], v[94:97]
	v_mfma_f32_16x16x32_bf16 v[90:93], v[126:129], v[208:211], v[90:93]
	v_mfma_f32_16x16x32_bf16 v[78:81], v[118:121], v[222:225], v[78:81]
	v_mfma_f32_16x16x32_bf16 v[74:77], v[126:129], v[222:225], v[74:77]
	v_mfma_f32_16x16x32_bf16 v[134:137], v[138:141], v[182:185], v[134:137]
	v_mfma_f32_16x16x32_bf16 v[130:133], v[154:157], v[182:185], v[130:133]
	v_mfma_f32_16x16x32_bf16 v[102:105], v[138:141], v[190:193], v[102:105]
	v_mfma_f32_16x16x32_bf16 v[98:101], v[154:157], v[190:193], v[98:101]
	v_mfma_f32_16x16x32_bf16 v[86:89], v[138:141], v[204:207], v[86:89]
	v_mfma_f32_16x16x32_bf16 v[82:85], v[154:157], v[204:207], v[82:85]
	v_mfma_f32_16x16x32_bf16 v[70:73], v[138:141], v[212:215], v[70:73]
	v_mfma_f32_16x16x32_bf16 v[66:69], v[154:157], v[212:215], v[66:69]
	v_mfma_f32_16x16x32_bf16 v[134:137], v[142:145], v[186:189], v[134:137]
	v_mfma_f32_16x16x32_bf16 v[130:133], v[178:181], v[186:189], v[130:133]
	v_mfma_f32_16x16x32_bf16 v[102:105], v[142:145], v[200:203], v[102:105]
	v_mfma_f32_16x16x32_bf16 v[98:101], v[178:181], v[200:203], v[98:101]
	v_mfma_f32_16x16x32_bf16 v[86:89], v[142:145], v[208:211], v[86:89]
	v_mfma_f32_16x16x32_bf16 v[82:85], v[178:181], v[208:211], v[82:85]
	v_mfma_f32_16x16x32_bf16 v[70:73], v[142:145], v[222:225], v[70:73]
	v_mfma_f32_16x16x32_bf16 v[66:69], v[178:181], v[222:225], v[66:69]
	s_barrier
	s_add_i32 s36, s36, s62
	v_lshl_add_u64 v[194:195], s[56:57], 0, v[162:163]
	s_mov_b32 m0, s36
	ds_read_b128 v[182:185], v199 offset:16384
	ds_read_b128 v[186:189], v199 offset:17408
	ds_read_b128 v[190:193], v199 offset:18432
	ds_read_b128 v[200:203], v199 offset:19456
	ds_read_b128 v[204:207], v199 offset:20480
	ds_read_b128 v[208:211], v199 offset:21504
	ds_read_b128 v[212:215], v199 offset:22528
	ds_read_b128 v[222:225], v199 offset:23552
	global_load_lds_dwordx4 v[194:195], off
	s_add_i32 m0, s36, 0x2000
	s_add_u32 s36, s56, 0x160000
	v_lshl_add_u64 v[216:217], s[56:57], 0, v[172:173]
	s_addc_u32 s37, s57, 0
	s_add_i32 s38, s38, s62
	global_load_lds_dwordx4 v[216:217], off
	v_lshl_add_u64 v[226:227], s[36:37], 0, v[162:163]
	s_mov_b32 m0, s38
	s_nop 0
	global_load_lds_dwordx4 v[226:227], off
	v_lshl_add_u64 v[226:227], s[36:37], 0, v[172:173]
	s_add_i32 m0, s38, 0x2000
	s_nop 0
	global_load_lds_dwordx4 v[226:227], off
	v_lshl_add_u64 v[226:227], s[58:59], 0, v[158:159]
	s_mov_b32 m0, s63
	s_nop 0
	global_load_lds_dwordx4 v[226:227], off
	v_lshl_add_u64 v[226:227], s[58:59], 0, v[160:161]
	s_mov_b32 m0, s64
	s_nop 0
	global_load_lds_dwordx4 v[226:227], off
	s_waitcnt vmcnt(56)
	s_cmp_eq_i32 s82, -2
	s_cselect_b32 s100, s101, 0
	s_cmp_lg_u32 s100, 0
	s_cbranch_scc1 .Lrw_skip437_1
	s_waitcnt vmcnt(8)
.Lrw_skip437_1:
	s_waitcnt lgkmcnt(0)
	s_barrier
	v_mfma_f32_16x16x32_bf16 v[62:65], v[114:117], v[182:185], v[62:65]
	v_mfma_f32_16x16x32_bf16 v[58:61], v[122:125], v[182:185], v[58:61]
	v_mfma_f32_16x16x32_bf16 v[46:49], v[114:117], v[190:193], v[46:49]
	v_mfma_f32_16x16x32_bf16 v[42:45], v[122:125], v[190:193], v[42:45]
	v_mfma_f32_16x16x32_bf16 v[30:33], v[114:117], v[204:207], v[30:33]
	v_mfma_f32_16x16x32_bf16 v[26:29], v[122:125], v[204:207], v[26:29]
	v_mfma_f32_16x16x32_bf16 v[14:17], v[114:117], v[212:215], v[14:17]
	v_mfma_f32_16x16x32_bf16 v[10:13], v[122:125], v[212:215], v[10:13]
	v_mfma_f32_16x16x32_bf16 v[62:65], v[118:121], v[186:189], v[62:65]
	v_mfma_f32_16x16x32_bf16 v[58:61], v[126:129], v[186:189], v[58:61]
	v_mfma_f32_16x16x32_bf16 v[46:49], v[118:121], v[200:203], v[46:49]
	v_mfma_f32_16x16x32_bf16 v[42:45], v[126:129], v[200:203], v[42:45]
	v_mfma_f32_16x16x32_bf16 v[30:33], v[118:121], v[208:211], v[30:33]
	v_mfma_f32_16x16x32_bf16 v[26:29], v[126:129], v[208:211], v[26:29]
	v_mfma_f32_16x16x32_bf16 v[14:17], v[118:121], v[222:225], v[14:17]
	v_mfma_f32_16x16x32_bf16 v[10:13], v[126:129], v[222:225], v[10:13]
	v_mfma_f32_16x16x32_bf16 v[54:57], v[138:141], v[182:185], v[54:57]
	v_mfma_f32_16x16x32_bf16 v[50:53], v[154:157], v[182:185], v[50:53]
	v_mfma_f32_16x16x32_bf16 v[38:41], v[138:141], v[190:193], v[38:41]
	v_mfma_f32_16x16x32_bf16 v[34:37], v[154:157], v[190:193], v[34:37]
	v_mfma_f32_16x16x32_bf16 v[22:25], v[138:141], v[204:207], v[22:25]
	v_mfma_f32_16x16x32_bf16 v[18:21], v[154:157], v[204:207], v[18:21]
	v_mfma_f32_16x16x32_bf16 v[6:9], v[138:141], v[212:215], v[6:9]
	v_mfma_f32_16x16x32_bf16 v[2:5], v[154:157], v[212:215], v[2:5]
	v_mfma_f32_16x16x32_bf16 v[54:57], v[142:145], v[186:189], v[54:57]
	v_mfma_f32_16x16x32_bf16 v[50:53], v[178:181], v[186:189], v[50:53]
	v_mfma_f32_16x16x32_bf16 v[38:41], v[142:145], v[200:203], v[38:41]
	v_mfma_f32_16x16x32_bf16 v[34:37], v[178:181], v[200:203], v[34:37]
	v_mfma_f32_16x16x32_bf16 v[22:25], v[142:145], v[208:211], v[22:25]
	v_mfma_f32_16x16x32_bf16 v[18:21], v[178:181], v[208:211], v[18:21]
	v_mfma_f32_16x16x32_bf16 v[6:9], v[142:145], v[222:225], v[6:9]
	v_mfma_f32_16x16x32_bf16 v[2:5], v[178:181], v[222:225], v[2:5]
	s_barrier
	s_add_i32 s38, 0, 0x18000
	s_add_i32 s39, 0, 0x1c000
	v_add_u32_e32 v126, s38, v197
	v_add_u32_e32 v168, s39, v197
	ds_read_b128 v[114:117], v126
	ds_read_b128 v[118:121], v126 offset:1024
	ds_read_b128 v[122:125], v126 offset:2048
	ds_read_b128 v[126:129], v126 offset:3072
	ds_read_b128 v[138:141], v168
	ds_read_b128 v[142:145], v168 offset:1024
	ds_read_b128 v[154:157], v168 offset:2048
	ds_read_b128 v[178:181], v168 offset:3072
	s_add_u32 s36, s58, 0x4000
	s_addc_u32 s37, s59, 0
	s_mov_b32 m0, s65
	v_lshl_add_u64 v[226:227], s[36:37], 0, v[158:159]
	ds_read_b128 v[182:185], v199 offset:32768
	ds_read_b128 v[186:189], v199 offset:33792
	ds_read_b128 v[190:193], v199 offset:34816
	ds_read_b128 v[200:203], v199 offset:35840
	ds_read_b128 v[204:207], v199 offset:36864
	ds_read_b128 v[208:211], v199 offset:37888
	ds_read_b128 v[212:215], v199 offset:38912
	ds_read_b128 v[222:225], v199 offset:39936
	global_load_lds_dwordx4 v[226:227], off
	v_lshl_add_u64 v[226:227], s[36:37], 0, v[160:161]
	s_mov_b32 m0, s66
	s_nop 0
	global_load_lds_dwordx4 v[226:227], off
	s_waitcnt vmcnt(8)
	s_waitcnt lgkmcnt(0)
	s_barrier
	v_mfma_f32_16x16x32_bf16 v[150:153], v[114:117], v[182:185], v[150:153]
	v_mfma_f32_16x16x32_bf16 v[146:149], v[122:125], v[182:185], v[146:149]
	v_mfma_f32_16x16x32_bf16 v[110:113], v[114:117], v[190:193], v[110:113]
	v_mfma_f32_16x16x32_bf16 v[106:109], v[122:125], v[190:193], v[106:109]
	v_mfma_f32_16x16x32_bf16 v[94:97], v[114:117], v[204:207], v[94:97]
	v_mfma_f32_16x16x32_bf16 v[90:93], v[122:125], v[204:207], v[90:93]
	v_mfma_f32_16x16x32_bf16 v[78:81], v[114:117], v[212:215], v[78:81]
	v_mfma_f32_16x16x32_bf16 v[74:77], v[122:125], v[212:215], v[74:77]
	v_mfma_f32_16x16x32_bf16 v[150:153], v[118:121], v[186:189], v[150:153]
	v_mfma_f32_16x16x32_bf16 v[146:149], v[126:129], v[186:189], v[146:149]
	v_mfma_f32_16x16x32_bf16 v[110:113], v[118:121], v[200:203], v[110:113]
	v_mfma_f32_16x16x32_bf16 v[106:109], v[126:129], v[200:203], v[106:109]
	v_mfma_f32_16x16x32_bf16 v[94:97], v[118:121], v[208:211], v[94:97]
	v_mfma_f32_16x16x32_bf16 v[90:93], v[126:129], v[208:211], v[90:93]
	v_mfma_f32_16x16x32_bf16 v[78:81], v[118:121], v[222:225], v[78:81]
	v_mfma_f32_16x16x32_bf16 v[74:77], v[126:129], v[222:225], v[74:77]
	v_mfma_f32_16x16x32_bf16 v[134:137], v[138:141], v[182:185], v[134:137]
	v_mfma_f32_16x16x32_bf16 v[130:133], v[154:157], v[182:185], v[130:133]
	v_mfma_f32_16x16x32_bf16 v[102:105], v[138:141], v[190:193], v[102:105]
	v_mfma_f32_16x16x32_bf16 v[98:101], v[154:157], v[190:193], v[98:101]
	v_mfma_f32_16x16x32_bf16 v[86:89], v[138:141], v[204:207], v[86:89]
	v_mfma_f32_16x16x32_bf16 v[82:85], v[154:157], v[204:207], v[82:85]
	v_mfma_f32_16x16x32_bf16 v[70:73], v[138:141], v[212:215], v[70:73]
	v_mfma_f32_16x16x32_bf16 v[66:69], v[154:157], v[212:215], v[66:69]
	v_mfma_f32_16x16x32_bf16 v[134:137], v[142:145], v[186:189], v[134:137]
	v_mfma_f32_16x16x32_bf16 v[130:133], v[178:181], v[186:189], v[130:133]
	v_mfma_f32_16x16x32_bf16 v[102:105], v[142:145], v[200:203], v[102:105]
	v_mfma_f32_16x16x32_bf16 v[98:101], v[178:181], v[200:203], v[98:101]
	v_mfma_f32_16x16x32_bf16 v[86:89], v[142:145], v[208:211], v[86:89]
	v_mfma_f32_16x16x32_bf16 v[82:85], v[178:181], v[208:211], v[82:85]
	v_mfma_f32_16x16x32_bf16 v[70:73], v[142:145], v[222:225], v[70:73]
	v_mfma_f32_16x16x32_bf16 v[66:69], v[178:181], v[222:225], v[66:69]
	s_barrier
	s_add_i32 s36, s38, s62
	v_lshl_add_u64 v[194:195], v[194:195], 0, s[44:45]
	s_mov_b32 m0, s36
	ds_read_b128 v[182:185], v199 offset:49152
	ds_read_b128 v[186:189], v199 offset:50176
	ds_read_b128 v[190:193], v199 offset:51200
	ds_read_b128 v[200:203], v199 offset:52224
	ds_read_b128 v[204:207], v199 offset:53248
	ds_read_b128 v[208:211], v199 offset:54272
	ds_read_b128 v[212:215], v199 offset:55296
	ds_read_b128 v[222:225], v199 offset:56320
	global_load_lds_dwordx4 v[194:195], off
	s_add_i32 m0, s36, 0x2000
	s_add_u32 s36, s56, 0x160080
	v_lshl_add_u64 v[194:195], v[216:217], 0, s[44:45]
	s_addc_u32 s37, s57, 0
	s_add_i32 s38, s39, s62
	global_load_lds_dwordx4 v[194:195], off
	v_lshl_add_u64 v[194:195], s[36:37], 0, v[162:163]
	s_mov_b32 m0, s38
	s_nop 0
	global_load_lds_dwordx4 v[194:195], off
	v_lshl_add_u64 v[194:195], s[36:37], 0, v[172:173]
	s_add_i32 m0, s38, 0x2000
	s_nop 0
	global_load_lds_dwordx4 v[194:195], off
	v_lshl_add_u64 v[194:195], s[26:27], 0, v[158:159]
	s_mov_b32 m0, s67
	s_nop 0
	global_load_lds_dwordx4 v[194:195], off
	v_lshl_add_u64 v[194:195], s[26:27], 0, v[160:161]
	s_mov_b32 m0, s68
	s_nop 0
	global_load_lds_dwordx4 v[194:195], off
	s_waitcnt vmcnt(8)
	s_waitcnt lgkmcnt(0)
	s_barrier
	v_mfma_f32_16x16x32_bf16 v[62:65], v[114:117], v[182:185], v[62:65]
	v_mfma_f32_16x16x32_bf16 v[58:61], v[122:125], v[182:185], v[58:61]
	v_mfma_f32_16x16x32_bf16 v[46:49], v[114:117], v[190:193], v[46:49]
	v_mfma_f32_16x16x32_bf16 v[42:45], v[122:125], v[190:193], v[42:45]
	v_mfma_f32_16x16x32_bf16 v[30:33], v[114:117], v[204:207], v[30:33]
	v_mfma_f32_16x16x32_bf16 v[26:29], v[122:125], v[204:207], v[26:29]
	v_mfma_f32_16x16x32_bf16 v[14:17], v[114:117], v[212:215], v[14:17]
	v_mfma_f32_16x16x32_bf16 v[10:13], v[122:125], v[212:215], v[10:13]
	v_mfma_f32_16x16x32_bf16 v[62:65], v[118:121], v[186:189], v[62:65]
	v_mfma_f32_16x16x32_bf16 v[58:61], v[126:129], v[186:189], v[58:61]
	v_mfma_f32_16x16x32_bf16 v[46:49], v[118:121], v[200:203], v[46:49]
	v_mfma_f32_16x16x32_bf16 v[42:45], v[126:129], v[200:203], v[42:45]
	v_mfma_f32_16x16x32_bf16 v[30:33], v[118:121], v[208:211], v[30:33]
	v_mfma_f32_16x16x32_bf16 v[26:29], v[126:129], v[208:211], v[26:29]
	v_mfma_f32_16x16x32_bf16 v[14:17], v[118:121], v[222:225], v[14:17]
	v_mfma_f32_16x16x32_bf16 v[10:13], v[126:129], v[222:225], v[10:13]
	v_mfma_f32_16x16x32_bf16 v[54:57], v[138:141], v[182:185], v[54:57]
	v_mfma_f32_16x16x32_bf16 v[50:53], v[154:157], v[182:185], v[50:53]
	v_mfma_f32_16x16x32_bf16 v[38:41], v[138:141], v[190:193], v[38:41]
	v_mfma_f32_16x16x32_bf16 v[34:37], v[154:157], v[190:193], v[34:37]
	v_mfma_f32_16x16x32_bf16 v[22:25], v[138:141], v[204:207], v[22:25]
	v_mfma_f32_16x16x32_bf16 v[18:21], v[154:157], v[204:207], v[18:21]
	v_mfma_f32_16x16x32_bf16 v[6:9], v[138:141], v[212:215], v[6:9]
	v_mfma_f32_16x16x32_bf16 v[2:5], v[154:157], v[212:215], v[2:5]
	v_mfma_f32_16x16x32_bf16 v[54:57], v[142:145], v[186:189], v[54:57]
	v_mfma_f32_16x16x32_bf16 v[50:53], v[178:181], v[186:189], v[50:53]
	v_mfma_f32_16x16x32_bf16 v[38:41], v[142:145], v[200:203], v[38:41]
	v_mfma_f32_16x16x32_bf16 v[34:37], v[178:181], v[200:203], v[34:37]
	v_mfma_f32_16x16x32_bf16 v[22:25], v[142:145], v[208:211], v[22:25]
	v_mfma_f32_16x16x32_bf16 v[18:21], v[178:181], v[208:211], v[18:21]
	v_mfma_f32_16x16x32_bf16 v[6:9], v[142:145], v[222:225], v[6:9]
	v_mfma_f32_16x16x32_bf16 v[2:5], v[178:181], v[222:225], v[2:5]
	s_barrier
	s_add_i32 s82, s82, 2
	s_add_u32 s24, s24, 0x10000
	s_addc_u32 s25, s25, 0
	s_add_u32 s80, s80, 0x100
	s_addc_u32 s81, s81, 0
	s_cmpk_gt_u32 s82, 0x55
	s_cbranch_scc0 .LBB0_437
	s_and_b64 vcc, exec, s[18:19]
	s_cbranch_vccz .LBB0_440
	s_barrier

.LBB0_456:
	s_or_b64 exec, exec, s[24:25]
	s_and_b64 vcc, exec, s[6:7]
	s_mov_b64 s[6:7], -1
	s_cbranch_vccnz .LBB0_423
	s_mov_b32 s101, 1
	s_andn2_b64 vcc, exec, s[8:9]
	s_cbranch_vccnz .LBB0_422
	s_barrier
	s_branch .LBB0_422

.LBB0_626:
	s_mov_b32 s101, 0
	s_add_u32 s12, s8, 0x32000000
	v_bfe_u32 v17, v157, 4, 2
	s_addc_u32 s13, s9, 0
	s_lshl_b64 s[14:15], s[54:55], 3
	v_and_b32_e32 v16, 15, v157
	v_lshlrev_b32_e32 v18, 4, v17
	s_add_u32 s14, s6, s14
	v_lshl_or_b32 v159, s4, 6, v16
	v_lshl_or_b32 v16, v16, 6, v18
	v_lshlrev_b32_e32 v18, 2, v157
	s_addc_u32 s15, s7, s15
	s_lshl_b32 s4, s4, 13
	v_and_b32_e32 v18, 32, v18
	v_bitop3_b32 v19, v16, s4, v18 bitop3:0xde
	s_lshl_b32 s4, s5, 5
	s_and_b32 s6, s4, 0x60
	s_add_i32 m0, s41, 0x18000
	v_lshl_add_u64 v[8:9], v[8:9], 0, s[44:45]
	s_lshl_b32 s4, s6, 7
	s_waitcnt vmcnt(2)
	s_barrier
	global_load_lds_dwordx4 v[8:9], off
	v_lshl_add_u64 v[6:7], v[6:7], 0, s[44:45]
	s_add_i32 m0, s41, 0x1a000
	s_add_i32 s76, s41, 0x8000
	s_add_i32 s77, s41, 0xa000
	v_bitop3_b32 v161, v16, s4, v18 bitop3:0xde
	global_load_lds_dwordx4 v[6:7], off
	v_lshl_add_u64 v[2:3], v[2:3], 0, s[44:45]
	s_mov_b32 m0, s76
	s_add_u32 s4, s60, 0x80080
	global_load_lds_dwordx4 v[2:3], off
	v_lshl_add_u64 v[2:3], v[4:5], 0, s[44:45]
	s_mov_b32 m0, s77
	s_addc_u32 s5, s61, 0
	global_load_lds_dwordx4 v[2:3], off
	s_add_i32 m0, s41, 0x1c000
	v_lshl_add_u64 v[2:3], s[4:5], 0, v[162:163]
	global_load_lds_dwordx4 v[2:3], off
	v_lshl_add_u64 v[2:3], s[4:5], 0, v[134:135]
	s_add_i32 m0, s41, 0x1e000
	s_and_b32 s4, s2, 7
	global_load_lds_dwordx4 v[2:3], off
	v_lshlrev_b32_e32 v2, 15, v13
	v_and_b32_e32 v2, 0xffff0000, v2
	s_ashr_i32 s79, s2, 3
	v_lshl_add_u32 v2, v14, 12, v2
	v_and_b32_e32 v3, 1, v13
	s_lshl_b32 s5, s4, 3
	s_and_b32 s7, s79, 7
	v_lshl_or_b32 v2, v3, 6, v2
	s_ashr_i32 s78, s2, 31
	s_or_b32 s80, s5, s7
	s_lshl_b32 s81, s4, 1
	v_lshl_add_u32 v136, v15, 1, v2
	v_lshlrev_b32_e32 v2, 15, v10
	s_cmpk_lt_u32 s16, 0x100
	v_and_b32_e32 v2, 0xffff0000, v2
	s_waitcnt vmcnt(6)
	s_cselect_b64 s[16:17], -1, 0
	s_add_i32 s4, 0, 0x20940
	v_lshl_add_u32 v2, v11, 12, v2
	v_and_b32_e32 v3, 1, v10
	s_add_u32 s18, s14, 0x20000
	v_lshl_or_b32 v2, v3, 6, v2
	v_lshl_add_u32 v175, v159, 3, s4
	s_mov_b32 s27, 0
	v_cmp_eq_u32_e64 s[4:5], 0, v17
	s_addc_u32 s19, s15, 0
	v_lshl_or_b32 v177, v17, 3, s6
	v_mov_b32_e32 v137, v163
	v_lshl_add_u32 v138, v12, 1, v2
	v_mov_b32_e32 v139, v163
	v_add_u32_e32 v179, 0, v19
	s_mov_b32 s82, 0
	s_mov_b32 s31, 0x2f800000
	s_barrier
	s_branch .LBB0_629

.LBB0_643:
	s_add_u32 s36, s58, 0xfff80080
	s_addc_u32 s37, s59, -1
	s_add_i32 s38, 0, 0x10000
	s_cmp_eq_u32 s64, 28
	s_cselect_b32 s63, s23, s37
	s_cselect_b32 s62, s22, s36
	s_cselect_b32 s61, s25, s57
	s_cselect_b32 s60, s24, s21
	s_add_i32 s39, 0, 0x14000
	v_add_u32_e32 v152, s38, v161
	v_add_u32_e32 v156, s39, v161
	ds_read_b128 v[140:143], v152
	ds_read_b128 v[144:147], v152 offset:1024
	ds_read_b128 v[148:151], v152 offset:2048
	ds_read_b128 v[152:155], v152 offset:3072
	ds_read_b128 v[180:183], v156
	ds_read_b128 v[184:187], v156 offset:1024
	ds_read_b128 v[188:191], v156 offset:2048
	ds_read_b128 v[192:195], v156 offset:3072
	v_lshl_add_u64 v[172:173], s[58:59], 0, v[138:139]
	s_add_i32 m0, s41, 0xc000
	ds_read_b128 v[196:199], v179
	ds_read_b128 v[200:203], v179 offset:1024
	ds_read_b128 v[204:207], v179 offset:2048
	ds_read_b128 v[208:211], v179 offset:3072
	ds_read_b128 v[212:215], v179 offset:4096
	ds_read_b128 v[222:225], v179 offset:5120
	ds_read_b128 v[226:229], v179 offset:6144
	ds_read_b128 v[230:233], v179 offset:7168
	global_load_lds_dwordx4 v[172:173], off
	v_lshl_add_u64 v[172:173], s[58:59], 0, v[136:137]
	s_add_i32 m0, s41, 0xe000
	s_nop 0
	global_load_lds_dwordx4 v[172:173], off
	s_waitcnt vmcnt(24)
	s_cmp_eq_i32 s64, -2
	s_cselect_b32 s100, s101, 0
	s_cmp_lg_u32 s100, 0
	s_cbranch_scc1 .Lrw_skip643_0
	s_waitcnt vmcnt(8)
.Lrw_skip643_0:
	s_waitcnt lgkmcnt(0)
	s_barrier
	v_mfma_f32_16x16x32_bf16 v[126:129], v[140:143], v[196:199], v[126:129]
	v_mfma_f32_16x16x32_bf16 v[86:89], v[148:151], v[196:199], v[86:89]
	v_mfma_f32_16x16x32_bf16 v[118:121], v[140:143], v[204:207], v[118:121]
	v_mfma_f32_16x16x32_bf16 v[94:97], v[148:151], v[204:207], v[94:97]
	v_mfma_f32_16x16x32_bf16 v[106:109], v[140:143], v[212:215], v[106:109]
	v_mfma_f32_16x16x32_bf16 v[102:105], v[148:151], v[212:215], v[102:105]
	v_mfma_f32_16x16x32_bf16 v[78:81], v[140:143], v[226:229], v[78:81]
	v_mfma_f32_16x16x32_bf16 v[74:77], v[148:151], v[226:229], v[74:77]
	v_mfma_f32_16x16x32_bf16 v[126:129], v[144:147], v[200:203], v[126:129]
	v_mfma_f32_16x16x32_bf16 v[86:89], v[152:155], v[200:203], v[86:89]
	v_mfma_f32_16x16x32_bf16 v[118:121], v[144:147], v[208:211], v[118:121]
	v_mfma_f32_16x16x32_bf16 v[94:97], v[152:155], v[208:211], v[94:97]
	v_mfma_f32_16x16x32_bf16 v[106:109], v[144:147], v[222:225], v[106:109]
	v_mfma_f32_16x16x32_bf16 v[102:105], v[152:155], v[222:225], v[102:105]
	v_mfma_f32_16x16x32_bf16 v[78:81], v[144:147], v[230:233], v[78:81]
	v_mfma_f32_16x16x32_bf16 v[74:77], v[152:155], v[230:233], v[74:77]
	v_mfma_f32_16x16x32_bf16 v[122:125], v[180:183], v[196:199], v[122:125]
	v_mfma_f32_16x16x32_bf16 v[98:101], v[188:191], v[196:199], v[98:101]
	v_mfma_f32_16x16x32_bf16 v[114:117], v[180:183], v[204:207], v[114:117]
	v_mfma_f32_16x16x32_bf16 v[110:113], v[188:191], v[204:207], v[110:113]
	v_mfma_f32_16x16x32_bf16 v[90:93], v[180:183], v[212:215], v[90:93]
	v_mfma_f32_16x16x32_bf16 v[82:85], v[188:191], v[212:215], v[82:85]
	v_mfma_f32_16x16x32_bf16 v[70:73], v[180:183], v[226:229], v[70:73]
	v_mfma_f32_16x16x32_bf16 v[66:69], v[188:191], v[226:229], v[66:69]
	v_mfma_f32_16x16x32_bf16 v[122:125], v[184:187], v[200:203], v[122:125]
	v_mfma_f32_16x16x32_bf16 v[98:101], v[192:195], v[200:203], v[98:101]
	v_mfma_f32_16x16x32_bf16 v[114:117], v[184:187], v[208:211], v[114:117]
	v_mfma_f32_16x16x32_bf16 v[110:113], v[192:195], v[208:211], v[110:113]
	v_mfma_f32_16x16x32_bf16 v[90:93], v[184:187], v[222:225], v[90:93]
	v_mfma_f32_16x16x32_bf16 v[82:85], v[192:195], v[222:225], v[82:85]
	v_mfma_f32_16x16x32_bf16 v[70:73], v[184:187], v[230:233], v[70:73]
	v_mfma_f32_16x16x32_bf16 v[66:69], v[192:195], v[230:233], v[66:69]
	s_barrier
	s_add_i32 s36, s38, s72
	v_lshl_add_u64 v[172:173], s[60:61], 0, v[162:163]
	s_mov_b32 m0, s36
	ds_read_b128 v[196:199], v179 offset:16384
	ds_read_b128 v[200:203], v179 offset:17408
	ds_read_b128 v[204:207], v179 offset:18432
	ds_read_b128 v[208:211], v179 offset:19456
	ds_read_b128 v[212:215], v179 offset:20480
	ds_read_b128 v[222:225], v179 offset:21504
	ds_read_b128 v[226:229], v179 offset:22528
	ds_read_b128 v[230:233], v179 offset:23552
	global_load_lds_dwordx4 v[172:173], off
	s_add_i32 m0, s36, 0x2000
	s_add_u32 s36, s60, 0x80000
	v_lshl_add_u64 v[216:217], s[60:61], 0, v[134:135]
	s_addc_u32 s37, s61, 0
	s_add_i32 s38, s39, s72
	global_load_lds_dwordx4 v[216:217], off
	v_lshl_add_u64 v[234:235], s[36:37], 0, v[162:163]
	s_mov_b32 m0, s38
	v_lshl_add_u64 v[236:237], s[62:63], 0, v[132:133]
	global_load_lds_dwordx4 v[234:235], off
	v_lshl_add_u64 v[234:235], s[36:37], 0, v[134:135]
	s_add_i32 m0, s38, 0x2000
	s_nop 0
	global_load_lds_dwordx4 v[234:235], off
	v_lshl_add_u64 v[234:235], s[62:63], 0, v[130:131]
	s_mov_b32 m0, s41
	s_nop 0
	global_load_lds_dwordx4 v[234:235], off
	s_mov_b32 m0, s66
	s_nop 0
	global_load_lds_dwordx4 v[236:237], off
	s_waitcnt vmcnt(24)
	s_cmp_eq_i32 s64, -2
	s_cselect_b32 s100, s101, 0
	s_cmp_lg_u32 s100, 0
	s_cbranch_scc1 .Lrw_skip643_1
	s_waitcnt vmcnt(8)
.Lrw_skip643_1:
	s_waitcnt lgkmcnt(0)
	s_barrier
	v_mfma_f32_16x16x32_bf16 v[62:65], v[140:143], v[196:199], v[62:65]
	v_mfma_f32_16x16x32_bf16 v[58:61], v[148:151], v[196:199], v[58:61]
	v_mfma_f32_16x16x32_bf16 v[46:49], v[140:143], v[204:207], v[46:49]
	v_mfma_f32_16x16x32_bf16 v[42:45], v[148:151], v[204:207], v[42:45]
	v_mfma_f32_16x16x32_bf16 v[30:33], v[140:143], v[212:215], v[30:33]
	v_mfma_f32_16x16x32_bf16 v[26:29], v[148:151], v[212:215], v[26:29]
	v_mfma_f32_16x16x32_bf16 v[14:17], v[140:143], v[226:229], v[14:17]
	v_mfma_f32_16x16x32_bf16 v[10:13], v[148:151], v[226:229], v[10:13]
	v_mfma_f32_16x16x32_bf16 v[62:65], v[144:147], v[200:203], v[62:65]
	v_mfma_f32_16x16x32_bf16 v[58:61], v[152:155], v[200:203], v[58:61]
	v_mfma_f32_16x16x32_bf16 v[46:49], v[144:147], v[208:211], v[46:49]
	v_mfma_f32_16x16x32_bf16 v[42:45], v[152:155], v[208:211], v[42:45]
	v_mfma_f32_16x16x32_bf16 v[30:33], v[144:147], v[222:225], v[30:33]
	v_mfma_f32_16x16x32_bf16 v[26:29], v[152:155], v[222:225], v[26:29]
	v_mfma_f32_16x16x32_bf16 v[14:17], v[144:147], v[230:233], v[14:17]
	v_mfma_f32_16x16x32_bf16 v[10:13], v[152:155], v[230:233], v[10:13]
	v_mfma_f32_16x16x32_bf16 v[54:57], v[180:183], v[196:199], v[54:57]
	v_mfma_f32_16x16x32_bf16 v[50:53], v[188:191], v[196:199], v[50:53]
	v_mfma_f32_16x16x32_bf16 v[38:41], v[180:183], v[204:207], v[38:41]
	v_mfma_f32_16x16x32_bf16 v[34:37], v[188:191], v[204:207], v[34:37]
	v_mfma_f32_16x16x32_bf16 v[22:25], v[180:183], v[212:215], v[22:25]
	v_mfma_f32_16x16x32_bf16 v[18:21], v[188:191], v[212:215], v[18:21]
	v_mfma_f32_16x16x32_bf16 v[6:9], v[180:183], v[226:229], v[6:9]
	v_mfma_f32_16x16x32_bf16 v[2:5], v[188:191], v[226:229], v[2:5]
	v_mfma_f32_16x16x32_bf16 v[54:57], v[184:187], v[200:203], v[54:57]
	v_mfma_f32_16x16x32_bf16 v[50:53], v[192:195], v[200:203], v[50:53]
	v_mfma_f32_16x16x32_bf16 v[38:41], v[184:187], v[208:211], v[38:41]
	v_mfma_f32_16x16x32_bf16 v[34:37], v[192:195], v[208:211], v[34:37]
	v_mfma_f32_16x16x32_bf16 v[22:25], v[184:187], v[222:225], v[22:25]
	v_mfma_f32_16x16x32_bf16 v[18:21], v[192:195], v[222:225], v[18:21]
	v_mfma_f32_16x16x32_bf16 v[6:9], v[184:187], v[230:233], v[6:9]
	v_mfma_f32_16x16x32_bf16 v[2:5], v[192:195], v[230:233], v[2:5]
	s_barrier
	s_add_i32 s38, 0, 0x18000
	s_add_i32 s39, 0, 0x1c000
	v_add_u32_e32 v152, s38, v161
	v_add_u32_e32 v156, s39, v161
	ds_read_b128 v[140:143], v152
	ds_read_b128 v[144:147], v152 offset:1024
	ds_read_b128 v[148:151], v152 offset:2048
	ds_read_b128 v[152:155], v152 offset:3072
	ds_read_b128 v[180:183], v156
	ds_read_b128 v[184:187], v156 offset:1024
	ds_read_b128 v[188:191], v156 offset:2048
	ds_read_b128 v[192:195], v156 offset:3072
	s_add_u32 s36, s62, 0x80000
	s_addc_u32 s37, s63, 0
	s_mov_b32 m0, s74
	v_lshl_add_u64 v[238:239], s[36:37], 0, v[130:131]
	ds_read_b128 v[196:199], v179 offset:32768
	ds_read_b128 v[200:203], v179 offset:33792
	ds_read_b128 v[204:207], v179 offset:34816
	ds_read_b128 v[208:211], v179 offset:35840
	ds_read_b128 v[212:215], v179 offset:36864
	ds_read_b128 v[222:225], v179 offset:37888
	ds_read_b128 v[226:229], v179 offset:38912
	ds_read_b128 v[230:233], v179 offset:39936
	global_load_lds_dwordx4 v[238:239], off
	v_lshl_add_u64 v[238:239], s[36:37], 0, v[132:133]
	s_mov_b32 m0, s75
	s_nop 0
	global_load_lds_dwordx4 v[238:239], off
	s_waitcnt vmcnt(8)
	s_waitcnt lgkmcnt(0)
	s_barrier
	v_mfma_f32_16x16x32_bf16 v[126:129], v[140:143], v[196:199], v[126:129]
	v_mfma_f32_16x16x32_bf16 v[86:89], v[148:151], v[196:199], v[86:89]
	v_mfma_f32_16x16x32_bf16 v[118:121], v[140:143], v[204:207], v[118:121]
	v_mfma_f32_16x16x32_bf16 v[94:97], v[148:151], v[204:207], v[94:97]
	v_mfma_f32_16x16x32_bf16 v[106:109], v[140:143], v[212:215], v[106:109]
	v_mfma_f32_16x16x32_bf16 v[102:105], v[148:151], v[212:215], v[102:105]
	v_mfma_f32_16x16x32_bf16 v[78:81], v[140:143], v[226:229], v[78:81]
	v_mfma_f32_16x16x32_bf16 v[74:77], v[148:151], v[226:229], v[74:77]
	v_mfma_f32_16x16x32_bf16 v[126:129], v[144:147], v[200:203], v[126:129]
	v_mfma_f32_16x16x32_bf16 v[86:89], v[152:155], v[200:203], v[86:89]
	v_mfma_f32_16x16x32_bf16 v[118:121], v[144:147], v[208:211], v[118:121]
	v_mfma_f32_16x16x32_bf16 v[94:97], v[152:155], v[208:211], v[94:97]
	v_mfma_f32_16x16x32_bf16 v[106:109], v[144:147], v[222:225], v[106:109]
	v_mfma_f32_16x16x32_bf16 v[102:105], v[152:155], v[222:225], v[102:105]
	v_mfma_f32_16x16x32_bf16 v[78:81], v[144:147], v[230:233], v[78:81]
	v_mfma_f32_16x16x32_bf16 v[74:77], v[152:155], v[230:233], v[74:77]
	v_mfma_f32_16x16x32_bf16 v[122:125], v[180:183], v[196:199], v[122:125]
	v_mfma_f32_16x16x32_bf16 v[98:101], v[188:191], v[196:199], v[98:101]
	v_mfma_f32_16x16x32_bf16 v[114:117], v[180:183], v[204:207], v[114:117]
	v_mfma_f32_16x16x32_bf16 v[110:113], v[188:191], v[204:207], v[110:113]
	v_mfma_f32_16x16x32_bf16 v[90:93], v[180:183], v[212:215], v[90:93]
	v_mfma_f32_16x16x32_bf16 v[82:85], v[188:191], v[212:215], v[82:85]
	v_mfma_f32_16x16x32_bf16 v[70:73], v[180:183], v[226:229], v[70:73]
	v_mfma_f32_16x16x32_bf16 v[66:69], v[188:191], v[226:229], v[66:69]
	v_mfma_f32_16x16x32_bf16 v[122:125], v[184:187], v[200:203], v[122:125]
	v_mfma_f32_16x16x32_bf16 v[98:101], v[192:195], v[200:203], v[98:101]
	v_mfma_f32_16x16x32_bf16 v[114:117], v[184:187], v[208:211], v[114:117]
	v_mfma_f32_16x16x32_bf16 v[110:113], v[192:195], v[208:211], v[110:113]
	v_mfma_f32_16x16x32_bf16 v[90:93], v[184:187], v[222:225], v[90:93]
	v_mfma_f32_16x16x32_bf16 v[82:85], v[192:195], v[222:225], v[82:85]
	v_mfma_f32_16x16x32_bf16 v[70:73], v[184:187], v[230:233], v[70:73]
	v_mfma_f32_16x16x32_bf16 v[66:69], v[192:195], v[230:233], v[66:69]
	s_barrier
	s_add_i32 s36, s38, s72
	v_lshl_add_u64 v[172:173], v[172:173], 0, s[44:45]
	s_mov_b32 m0, s36
	ds_read_b128 v[196:199], v179 offset:49152
	ds_read_b128 v[200:203], v179 offset:50176
	ds_read_b128 v[204:207], v179 offset:51200
	ds_read_b128 v[208:211], v179 offset:52224
	ds_read_b128 v[212:215], v179 offset:53248
	ds_read_b128 v[222:225], v179 offset:54272
	ds_read_b128 v[226:229], v179 offset:55296
	ds_read_b128 v[230:233], v179 offset:56320
	global_load_lds_dwordx4 v[172:173], off
	s_add_i32 m0, s36, 0x2000
	s_add_u32 s36, s60, 0x80080
	v_lshl_add_u64 v[172:173], v[216:217], 0, s[44:45]
	s_addc_u32 s37, s61, 0
	s_add_i32 s38, s39, s72
	global_load_lds_dwordx4 v[172:173], off
	v_lshl_add_u64 v[172:173], s[36:37], 0, v[162:163]
	s_mov_b32 m0, s38
	s_nop 0
	global_load_lds_dwordx4 v[172:173], off
	v_lshl_add_u64 v[172:173], s[36:37], 0, v[134:135]
	s_add_i32 m0, s38, 0x2000
	s_nop 0
	global_load_lds_dwordx4 v[172:173], off
	v_lshl_add_u64 v[172:173], v[234:235], 0, s[44:45]
	s_mov_b32 m0, s76
	s_nop 0
	global_load_lds_dwordx4 v[172:173], off
	v_lshl_add_u64 v[172:173], v[236:237], 0, s[44:45]
	s_mov_b32 m0, s77
	s_nop 0
	global_load_lds_dwordx4 v[172:173], off
	s_waitcnt vmcnt(8)
	s_waitcnt lgkmcnt(0)
	s_barrier
	v_mfma_f32_16x16x32_bf16 v[62:65], v[140:143], v[196:199], v[62:65]
	v_mfma_f32_16x16x32_bf16 v[58:61], v[148:151], v[196:199], v[58:61]
	v_mfma_f32_16x16x32_bf16 v[46:49], v[140:143], v[204:207], v[46:49]
	v_mfma_f32_16x16x32_bf16 v[42:45], v[148:151], v[204:207], v[42:45]
	v_mfma_f32_16x16x32_bf16 v[30:33], v[140:143], v[212:215], v[30:33]
	v_mfma_f32_16x16x32_bf16 v[26:29], v[148:151], v[212:215], v[26:29]
	v_mfma_f32_16x16x32_bf16 v[14:17], v[140:143], v[226:229], v[14:17]
	v_mfma_f32_16x16x32_bf16 v[10:13], v[148:151], v[226:229], v[10:13]
	v_mfma_f32_16x16x32_bf16 v[62:65], v[144:147], v[200:203], v[62:65]
	v_mfma_f32_16x16x32_bf16 v[58:61], v[152:155], v[200:203], v[58:61]
	v_mfma_f32_16x16x32_bf16 v[46:49], v[144:147], v[208:211], v[46:49]
	v_mfma_f32_16x16x32_bf16 v[42:45], v[152:155], v[208:211], v[42:45]
	v_mfma_f32_16x16x32_bf16 v[30:33], v[144:147], v[222:225], v[30:33]
	v_mfma_f32_16x16x32_bf16 v[26:29], v[152:155], v[222:225], v[26:29]
	v_mfma_f32_16x16x32_bf16 v[14:17], v[144:147], v[230:233], v[14:17]
	v_mfma_f32_16x16x32_bf16 v[10:13], v[152:155], v[230:233], v[10:13]
	v_mfma_f32_16x16x32_bf16 v[54:57], v[180:183], v[196:199], v[54:57]
	v_mfma_f32_16x16x32_bf16 v[50:53], v[188:191], v[196:199], v[50:53]
	v_mfma_f32_16x16x32_bf16 v[38:41], v[180:183], v[204:207], v[38:41]
	v_mfma_f32_16x16x32_bf16 v[34:37], v[188:191], v[204:207], v[34:37]
	v_mfma_f32_16x16x32_bf16 v[22:25], v[180:183], v[212:215], v[22:25]
	v_mfma_f32_16x16x32_bf16 v[18:21], v[188:191], v[212:215], v[18:21]
	v_mfma_f32_16x16x32_bf16 v[6:9], v[180:183], v[226:229], v[6:9]
	v_mfma_f32_16x16x32_bf16 v[2:5], v[188:191], v[226:229], v[2:5]
	v_mfma_f32_16x16x32_bf16 v[54:57], v[184:187], v[200:203], v[54:57]
	v_mfma_f32_16x16x32_bf16 v[50:53], v[192:195], v[200:203], v[50:53]
	v_mfma_f32_16x16x32_bf16 v[38:41], v[184:187], v[208:211], v[38:41]
	v_mfma_f32_16x16x32_bf16 v[34:37], v[192:195], v[208:211], v[34:37]
	v_mfma_f32_16x16x32_bf16 v[22:25], v[184:187], v[222:225], v[22:25]
	v_mfma_f32_16x16x32_bf16 v[18:21], v[192:195], v[222:225], v[18:21]
	v_mfma_f32_16x16x32_bf16 v[6:9], v[184:187], v[230:233], v[6:9]
	v_mfma_f32_16x16x32_bf16 v[2:5], v[192:195], v[230:233], v[2:5]
	s_barrier
	s_add_i32 s64, s64, 2
	s_add_u32 s21, s21, 0x100
	s_addc_u32 s57, s57, 0
	s_add_u32 s58, s58, 0x100
	s_addc_u32 s59, s59, 0
	s_cmp_gt_u32 s64, 29
	s_cbranch_scc0 .LBB0_643
	s_and_b64 vcc, exec, s[16:17]
	s_cbranch_vccz .LBB0_646
	s_barrier

.LBB0_667:
	s_and_b64 vcc, exec, s[6:7]
	s_mov_b64 s[6:7], -1
	s_cbranch_vccnz .LBB0_628
	s_ashr_i32 s21, s20, 31
	s_and_b32 s27, s82, 1
	s_lshl_b64 s[6:7], s[20:21], 11
	v_mov_b32_e32 v2, v157
	s_add_u32 s6, s29, s6
	s_addc_u32 s7, s71, s7
	s_waitcnt lgkmcnt(0)
	v_ashrrev_i32_e32 v3, 31, v2
	v_lshl_add_u64 v[2:3], v[2:3], 2, s[6:7]
	s_mul_i32 s6, s27, 0x1400
	s_add_i32 m0, s73, s6
	s_mov_b32 s101, 1
	s_andn2_b64 vcc, exec, s[10:11]
	global_load_lds_dword v[2:3], off
	s_cbranch_vccnz .LBB0_627
	s_barrier
	s_branch .LBB0_627

.LBB0_683:
	s_mov_b32 s101, 0
	s_lshl_b32 s5, s5, 5
	s_and_b32 s70, s5, 0x60
	s_add_i32 m0, s25, 0x18000
	v_lshl_add_u64 v[8:9], v[8:9], 0, s[44:45]
	s_lshl_b32 s16, s13, 13
	s_lshl_b32 s5, s70, 7
	s_waitcnt vmcnt(2)
	s_barrier
	global_load_lds_dwordx4 v[8:9], off
	v_lshl_add_u64 v[6:7], v[6:7], 0, s[44:45]
	s_add_i32 m0, s25, 0x1a000
	s_add_i32 s71, s25, 0x8000
	s_add_i32 s72, s25, 0xa000
	global_load_lds_dwordx4 v[6:7], off
	v_lshl_add_u64 v[2:3], v[2:3], 0, s[44:45]
	s_mov_b32 m0, s71
	s_add_u32 s14, s56, 0x80080
	global_load_lds_dwordx4 v[2:3], off
	v_lshl_add_u64 v[2:3], v[4:5], 0, s[44:45]
	s_mov_b32 m0, s72
	s_addc_u32 s15, s57, 0
	global_load_lds_dwordx4 v[2:3], off
	s_add_i32 m0, s25, 0x1c000
	v_lshl_add_u64 v[2:3], s[14:15], 0, v[162:163]
	global_load_lds_dwordx4 v[2:3], off
	v_lshl_add_u64 v[2:3], s[14:15], 0, v[134:135]
	s_add_i32 m0, s25, 0x1e000
	v_lshlrev_b32_e32 v4, 2, v141
	global_load_lds_dwordx4 v[2:3], off
	v_and_b32_e32 v2, 15, v141
	v_lshrrev_b32_e32 v3, 1, v141
	v_lshl_or_b32 v143, s13, 6, v2
	v_and_b32_e32 v145, 24, v3
	v_lshlrev_b32_e32 v3, 1, v145
	v_lshlrev_b32_e32 v147, 2, v143
	v_lshl_or_b32 v2, v2, 6, v3
	v_and_b32_e32 v3, 32, v147
	v_and_b32_e32 v4, 32, v4
	v_bitop3_b32 v3, v2, s16, v3 bitop3:0xde
	v_bitop3_b32 v149, v2, s5, v4 bitop3:0xde
	v_or_b32_e32 v2, 16, v143
	v_lshlrev_b32_e32 v153, 3, v2
	v_lshlrev_b32_e32 v155, 2, v2
	v_or_b32_e32 v2, 32, v143
	v_lshlrev_b32_e32 v176, 3, v2
	v_lshlrev_b32_e32 v177, 2, v2
	v_or_b32_e32 v2, 48, v143
	v_lshlrev_b32_e32 v178, 3, v2
	v_lshlrev_b32_e32 v179, 2, v2
	v_add_u32_e32 v2, 0x80, v143
	v_lshlrev_b32_e32 v180, 3, v2
	v_lshlrev_b32_e32 v181, 2, v2
	v_add_u32_e32 v2, 0x90, v143
	v_lshlrev_b32_e32 v182, 3, v2
	v_lshlrev_b32_e32 v183, 2, v2
	v_add_u32_e32 v2, 0xa0, v143
	v_lshlrev_b32_e32 v184, 3, v2
	v_lshlrev_b32_e32 v185, 2, v2
	v_add_u32_e32 v2, 0xb0, v143
	v_lshlrev_b32_e32 v186, 3, v2
	v_lshlrev_b32_e32 v187, 2, v2
	v_lshlrev_b32_e32 v2, 14, v13
	s_and_b32 s76, s2, 7
	s_ashr_i32 s74, s2, 3
	v_and_b32_e32 v2, 0xffff8000, v2
	s_lshl_b32 s5, s76, 3
	s_and_b32 s13, s74, 7
	v_lshl_add_u32 v2, v14, 11, v2
	v_and_b32_e32 v4, 1, v13
	s_ashr_i32 s73, s2, 31
	s_or_b32 s75, s5, s13
	v_lshl_or_b32 v2, v4, 6, v2
	s_cmpk_lt_u32 s12, 0x100
	v_lshl_add_u32 v136, v15, 1, v2
	v_lshlrev_b32_e32 v2, 14, v10
	s_cselect_b64 s[12:13], -1, 0
	s_add_u32 s77, s8, 0x6b000000
	v_and_b32_e32 v2, 0xffff8000, v2
	s_waitcnt vmcnt(6)
	s_addc_u32 s78, s9, 0
	v_lshl_add_u32 v2, v11, 11, v2
	v_and_b32_e32 v4, 1, v10
	s_add_u32 s79, s8, s4
	v_lshl_or_b32 v2, v4, 6, v2
	s_mul_i32 s76, s76, 3
	v_lshlrev_b32_e32 v151, 3, v143
	s_addc_u32 s80, s9, 0
	v_or_b32_e32 v188, s70, v145
	v_mov_b32_e32 v137, v163
	v_lshl_add_u32 v138, v12, 1, v2
	v_mov_b32_e32 v139, v163
	s_mov_b32 s82, 0
	v_add_u32_e32 v189, 0, v3
	s_mov_b32 s81, 0
	s_barrier
	s_branch .LBB0_686

.LBB0_696:
	s_add_u32 s36, s26, 0xfffc0080
	s_addc_u32 s37, s27, -1
	s_add_i32 s38, 0, 0x10000
	s_cmp_eq_u32 s60, 12
	s_cselect_b32 s59, s19, s37
	s_cselect_b32 s58, s18, s36
	v_add_u32_e32 v140, s38, v149
	s_cselect_b32 s57, s21, s17
	s_cselect_b32 s56, s20, s15
	s_add_i32 s39, 0, 0x14000
	ds_read_b128 v[156:159], v140
	ds_read_b128 v[172:175], v140 offset:1024
	ds_read_b128 v[190:193], v140 offset:2048
	ds_read_b128 v[194:197], v140 offset:3072
	v_add_u32_e32 v140, s39, v149
	ds_read_b128 v[198:201], v140
	ds_read_b128 v[202:205], v140 offset:1024
	ds_read_b128 v[206:209], v140 offset:2048
	ds_read_b128 v[210:213], v140 offset:3072
	v_lshl_add_u64 v[160:161], s[26:27], 0, v[138:139]
	s_add_i32 m0, s25, 0xc000
	ds_read_b128 v[214:217], v189
	ds_read_b128 v[222:225], v189 offset:1024
	ds_read_b128 v[226:229], v189 offset:2048
	ds_read_b128 v[230:233], v189 offset:3072
	ds_read_b128 v[234:237], v189 offset:4096
	ds_read_b128 v[238:241], v189 offset:5120
	ds_read_b128 v[242:245], v189 offset:6144
	ds_read_b128 v[246:249], v189 offset:7168
	global_load_lds_dwordx4 v[160:161], off
	v_lshl_add_u64 v[160:161], s[26:27], 0, v[136:137]
	s_add_i32 m0, s25, 0xe000
	s_nop 0
	global_load_lds_dwordx4 v[160:161], off
	s_waitcnt vmcnt(25)
	s_cmp_eq_i32 s60, -2
	s_cselect_b32 s100, s101, 0
	s_cmp_lg_u32 s100, 0
	s_cbranch_scc1 .Lrw_skip696_0
	s_waitcnt vmcnt(8)
.Lrw_skip696_0:
	s_waitcnt lgkmcnt(0)
	s_barrier
	v_mfma_i32_16x16x64_i8 v[126:129], v[156:159], v[214:217], v[126:129]
	v_mfma_i32_16x16x64_i8 v[122:125], v[190:193], v[214:217], v[122:125]
	v_mfma_i32_16x16x64_i8 v[118:121], v[156:159], v[226:229], v[118:121]
	v_mfma_i32_16x16x64_i8 v[114:117], v[190:193], v[226:229], v[114:117]
	v_mfma_i32_16x16x64_i8 v[110:113], v[156:159], v[234:237], v[110:113]
	v_mfma_i32_16x16x64_i8 v[106:109], v[190:193], v[234:237], v[106:109]
	v_mfma_i32_16x16x64_i8 v[102:105], v[156:159], v[242:245], v[102:105]
	v_mfma_i32_16x16x64_i8 v[98:101], v[190:193], v[242:245], v[98:101]
	v_mfma_i32_16x16x64_i8 v[126:129], v[172:175], v[222:225], v[126:129]
	v_mfma_i32_16x16x64_i8 v[122:125], v[194:197], v[222:225], v[122:125]
	v_mfma_i32_16x16x64_i8 v[118:121], v[172:175], v[230:233], v[118:121]
	v_mfma_i32_16x16x64_i8 v[114:117], v[194:197], v[230:233], v[114:117]
	v_mfma_i32_16x16x64_i8 v[110:113], v[172:175], v[238:241], v[110:113]
	v_mfma_i32_16x16x64_i8 v[106:109], v[194:197], v[238:241], v[106:109]
	v_mfma_i32_16x16x64_i8 v[102:105], v[172:175], v[246:249], v[102:105]
	v_mfma_i32_16x16x64_i8 v[98:101], v[194:197], v[246:249], v[98:101]
	v_mfma_i32_16x16x64_i8 v[62:65], v[198:201], v[214:217], v[62:65]
	v_mfma_i32_16x16x64_i8 v[58:61], v[206:209], v[214:217], v[58:61]
	v_mfma_i32_16x16x64_i8 v[54:57], v[198:201], v[226:229], v[54:57]
	v_mfma_i32_16x16x64_i8 v[50:53], v[206:209], v[226:229], v[50:53]
	v_mfma_i32_16x16x64_i8 v[46:49], v[198:201], v[234:237], v[46:49]
	v_mfma_i32_16x16x64_i8 v[42:45], v[206:209], v[234:237], v[42:45]
	v_mfma_i32_16x16x64_i8 v[38:41], v[198:201], v[242:245], v[38:41]
	v_mfma_i32_16x16x64_i8 v[34:37], v[206:209], v[242:245], v[34:37]
	v_mfma_i32_16x16x64_i8 v[62:65], v[202:205], v[222:225], v[62:65]
	v_mfma_i32_16x16x64_i8 v[58:61], v[210:213], v[222:225], v[58:61]
	v_mfma_i32_16x16x64_i8 v[54:57], v[202:205], v[230:233], v[54:57]
	v_mfma_i32_16x16x64_i8 v[50:53], v[210:213], v[230:233], v[50:53]
	v_mfma_i32_16x16x64_i8 v[46:49], v[202:205], v[238:241], v[46:49]
	v_mfma_i32_16x16x64_i8 v[42:45], v[210:213], v[238:241], v[42:45]
	v_mfma_i32_16x16x64_i8 v[38:41], v[202:205], v[246:249], v[38:41]
	v_mfma_i32_16x16x64_i8 v[34:37], v[210:213], v[246:249], v[34:37]
	s_barrier
	s_add_i32 s36, s38, s23
	v_lshl_add_u64 v[160:161], s[56:57], 0, v[162:163]
	s_mov_b32 m0, s36
	ds_read_b128 v[214:217], v189 offset:16384
	ds_read_b128 v[222:225], v189 offset:17408
	ds_read_b128 v[226:229], v189 offset:18432
	ds_read_b128 v[230:233], v189 offset:19456
	ds_read_b128 v[234:237], v189 offset:20480
	ds_read_b128 v[238:241], v189 offset:21504
	ds_read_b128 v[242:245], v189 offset:22528
	ds_read_b128 v[246:249], v189 offset:23552
	global_load_lds_dwordx4 v[160:161], off
	s_add_i32 m0, s36, 0x2000
	s_add_u32 s36, s56, 0x80000
	v_lshl_add_u64 v[250:251], s[56:57], 0, v[134:135]
	s_addc_u32 s37, s57, 0
	s_add_i32 s38, s39, s23
	global_load_lds_dwordx4 v[250:251], off
	v_lshl_add_u64 v[252:253], s[36:37], 0, v[162:163]
	s_mov_b32 m0, s38
	v_lshl_add_u64 v[168:169], s[58:59], 0, v[132:133]
	global_load_lds_dwordx4 v[252:253], off
	v_lshl_add_u64 v[252:253], s[36:37], 0, v[134:135]
	s_add_i32 m0, s38, 0x2000
	s_nop 0
	global_load_lds_dwordx4 v[252:253], off
	v_lshl_add_u64 v[252:253], s[58:59], 0, v[130:131]
	s_mov_b32 m0, s25
	s_nop 0
	global_load_lds_dwordx4 v[252:253], off
	s_mov_b32 m0, s67
	s_nop 0
	global_load_lds_dwordx4 v[168:169], off
	s_waitcnt vmcnt(25)
	s_cmp_eq_i32 s60, -2
	s_cselect_b32 s100, s101, 0
	s_cmp_lg_u32 s100, 0
	s_cbranch_scc1 .Lrw_skip696_1
	s_waitcnt vmcnt(8)
.Lrw_skip696_1:
	s_waitcnt lgkmcnt(0)
	s_barrier
	v_mfma_i32_16x16x64_i8 v[94:97], v[156:159], v[214:217], v[94:97]
	v_mfma_i32_16x16x64_i8 v[90:93], v[190:193], v[214:217], v[90:93]
	v_mfma_i32_16x16x64_i8 v[86:89], v[156:159], v[226:229], v[86:89]
	v_mfma_i32_16x16x64_i8 v[82:85], v[190:193], v[226:229], v[82:85]
	v_mfma_i32_16x16x64_i8 v[78:81], v[156:159], v[234:237], v[78:81]
	v_mfma_i32_16x16x64_i8 v[74:77], v[190:193], v[234:237], v[74:77]
	v_mfma_i32_16x16x64_i8 v[70:73], v[156:159], v[242:245], v[70:73]
	v_mfma_i32_16x16x64_i8 v[66:69], v[190:193], v[242:245], v[66:69]
	v_mfma_i32_16x16x64_i8 v[94:97], v[172:175], v[222:225], v[94:97]
	v_mfma_i32_16x16x64_i8 v[90:93], v[194:197], v[222:225], v[90:93]
	v_mfma_i32_16x16x64_i8 v[86:89], v[172:175], v[230:233], v[86:89]
	v_mfma_i32_16x16x64_i8 v[82:85], v[194:197], v[230:233], v[82:85]
	v_mfma_i32_16x16x64_i8 v[78:81], v[172:175], v[238:241], v[78:81]
	v_mfma_i32_16x16x64_i8 v[74:77], v[194:197], v[238:241], v[74:77]
	v_mfma_i32_16x16x64_i8 v[70:73], v[172:175], v[246:249], v[70:73]
	v_mfma_i32_16x16x64_i8 v[66:69], v[194:197], v[246:249], v[66:69]
	v_mfma_i32_16x16x64_i8 v[30:33], v[198:201], v[214:217], v[30:33]
	v_mfma_i32_16x16x64_i8 v[26:29], v[206:209], v[214:217], v[26:29]
	v_mfma_i32_16x16x64_i8 v[22:25], v[198:201], v[226:229], v[22:25]
	v_mfma_i32_16x16x64_i8 v[18:21], v[206:209], v[226:229], v[18:21]
	v_mfma_i32_16x16x64_i8 v[14:17], v[198:201], v[234:237], v[14:17]
	v_mfma_i32_16x16x64_i8 v[10:13], v[206:209], v[234:237], v[10:13]
	v_mfma_i32_16x16x64_i8 v[6:9], v[198:201], v[242:245], v[6:9]
	v_mfma_i32_16x16x64_i8 v[2:5], v[206:209], v[242:245], v[2:5]
	v_mfma_i32_16x16x64_i8 v[30:33], v[202:205], v[222:225], v[30:33]
	v_mfma_i32_16x16x64_i8 v[26:29], v[210:213], v[222:225], v[26:29]
	v_mfma_i32_16x16x64_i8 v[22:25], v[202:205], v[230:233], v[22:25]
	v_mfma_i32_16x16x64_i8 v[18:21], v[210:213], v[230:233], v[18:21]
	v_mfma_i32_16x16x64_i8 v[14:17], v[202:205], v[238:241], v[14:17]
	v_mfma_i32_16x16x64_i8 v[10:13], v[210:213], v[238:241], v[10:13]
	v_mfma_i32_16x16x64_i8 v[6:9], v[202:205], v[246:249], v[6:9]
	v_mfma_i32_16x16x64_i8 v[2:5], v[210:213], v[246:249], v[2:5]
	s_barrier
	s_add_i32 s38, 0, 0x18000
	v_add_u32_e32 v140, s38, v149
	s_add_i32 s39, 0, 0x1c000
	ds_read_b128 v[156:159], v140
	ds_read_b128 v[172:175], v140 offset:1024
	ds_read_b128 v[190:193], v140 offset:2048
	ds_read_b128 v[194:197], v140 offset:3072
	v_add_u32_e32 v140, s39, v149
	ds_read_b128 v[198:201], v140
	ds_read_b128 v[202:205], v140 offset:1024
	ds_read_b128 v[206:209], v140 offset:2048
	ds_read_b128 v[210:213], v140 offset:3072
	s_add_u32 s36, s58, 0x40000
	s_addc_u32 s37, s59, 0
	s_mov_b32 m0, s68
	v_lshl_add_u64 v[170:171], s[36:37], 0, v[130:131]
	ds_read_b128 v[214:217], v189 offset:32768
	ds_read_b128 v[222:225], v189 offset:33792
	ds_read_b128 v[226:229], v189 offset:34816
	ds_read_b128 v[230:233], v189 offset:35840
	ds_read_b128 v[234:237], v189 offset:36864
	ds_read_b128 v[238:241], v189 offset:37888
	ds_read_b128 v[242:245], v189 offset:38912
	ds_read_b128 v[246:249], v189 offset:39936
	global_load_lds_dwordx4 v[170:171], off
	v_lshl_add_u64 v[170:171], s[36:37], 0, v[132:133]
	s_mov_b32 m0, s69
	s_nop 0
	global_load_lds_dwordx4 v[170:171], off
	s_waitcnt vmcnt(8)
	s_waitcnt lgkmcnt(0)
	s_barrier
	v_mfma_i32_16x16x64_i8 v[126:129], v[156:159], v[214:217], v[126:129]
	v_mfma_i32_16x16x64_i8 v[122:125], v[190:193], v[214:217], v[122:125]
	v_mfma_i32_16x16x64_i8 v[118:121], v[156:159], v[226:229], v[118:121]
	v_mfma_i32_16x16x64_i8 v[114:117], v[190:193], v[226:229], v[114:117]
	v_mfma_i32_16x16x64_i8 v[110:113], v[156:159], v[234:237], v[110:113]
	v_mfma_i32_16x16x64_i8 v[106:109], v[190:193], v[234:237], v[106:109]
	v_mfma_i32_16x16x64_i8 v[102:105], v[156:159], v[242:245], v[102:105]
	v_mfma_i32_16x16x64_i8 v[98:101], v[190:193], v[242:245], v[98:101]
	v_mfma_i32_16x16x64_i8 v[126:129], v[172:175], v[222:225], v[126:129]
	v_mfma_i32_16x16x64_i8 v[122:125], v[194:197], v[222:225], v[122:125]
	v_mfma_i32_16x16x64_i8 v[118:121], v[172:175], v[230:233], v[118:121]
	v_mfma_i32_16x16x64_i8 v[114:117], v[194:197], v[230:233], v[114:117]
	v_mfma_i32_16x16x64_i8 v[110:113], v[172:175], v[238:241], v[110:113]
	v_mfma_i32_16x16x64_i8 v[106:109], v[194:197], v[238:241], v[106:109]
	v_mfma_i32_16x16x64_i8 v[102:105], v[172:175], v[246:249], v[102:105]
	v_mfma_i32_16x16x64_i8 v[98:101], v[194:197], v[246:249], v[98:101]
	v_mfma_i32_16x16x64_i8 v[62:65], v[198:201], v[214:217], v[62:65]
	v_mfma_i32_16x16x64_i8 v[58:61], v[206:209], v[214:217], v[58:61]
	v_mfma_i32_16x16x64_i8 v[54:57], v[198:201], v[226:229], v[54:57]
	v_mfma_i32_16x16x64_i8 v[50:53], v[206:209], v[226:229], v[50:53]
	v_mfma_i32_16x16x64_i8 v[46:49], v[198:201], v[234:237], v[46:49]
	v_mfma_i32_16x16x64_i8 v[42:45], v[206:209], v[234:237], v[42:45]
	v_mfma_i32_16x16x64_i8 v[38:41], v[198:201], v[242:245], v[38:41]
	v_mfma_i32_16x16x64_i8 v[34:37], v[206:209], v[242:245], v[34:37]
	v_mfma_i32_16x16x64_i8 v[62:65], v[202:205], v[222:225], v[62:65]
	v_mfma_i32_16x16x64_i8 v[58:61], v[210:213], v[222:225], v[58:61]
	v_mfma_i32_16x16x64_i8 v[54:57], v[202:205], v[230:233], v[54:57]
	v_mfma_i32_16x16x64_i8 v[50:53], v[210:213], v[230:233], v[50:53]
	v_mfma_i32_16x16x64_i8 v[46:49], v[202:205], v[238:241], v[46:49]
	v_mfma_i32_16x16x64_i8 v[42:45], v[210:213], v[238:241], v[42:45]
	v_mfma_i32_16x16x64_i8 v[38:41], v[202:205], v[246:249], v[38:41]
	v_mfma_i32_16x16x64_i8 v[34:37], v[210:213], v[246:249], v[34:37]
	s_barrier
	s_add_i32 s36, s38, s23
	v_lshl_add_u64 v[160:161], v[160:161], 0, s[44:45]
	s_mov_b32 m0, s36
	ds_read_b128 v[214:217], v189 offset:49152
	ds_read_b128 v[222:225], v189 offset:50176
	ds_read_b128 v[226:229], v189 offset:51200
	ds_read_b128 v[230:233], v189 offset:52224
	ds_read_b128 v[234:237], v189 offset:53248
	ds_read_b128 v[238:241], v189 offset:54272
	ds_read_b128 v[242:245], v189 offset:55296
	ds_read_b128 v[246:249], v189 offset:56320
	global_load_lds_dwordx4 v[160:161], off
	s_add_i32 m0, s36, 0x2000
	s_add_u32 s36, s56, 0x80080
	v_lshl_add_u64 v[160:161], v[250:251], 0, s[44:45]
	s_addc_u32 s37, s57, 0
	s_add_i32 s38, s39, s23
	global_load_lds_dwordx4 v[160:161], off
	v_lshl_add_u64 v[160:161], s[36:37], 0, v[162:163]
	s_mov_b32 m0, s38
	s_nop 0
	global_load_lds_dwordx4 v[160:161], off
	v_lshl_add_u64 v[160:161], s[36:37], 0, v[134:135]
	s_add_i32 m0, s38, 0x2000
	s_nop 0
	global_load_lds_dwordx4 v[160:161], off
	v_lshl_add_u64 v[160:161], v[252:253], 0, s[44:45]
	s_mov_b32 m0, s71
	s_nop 0
	global_load_lds_dwordx4 v[160:161], off
	v_lshl_add_u64 v[160:161], v[168:169], 0, s[44:45]
	s_mov_b32 m0, s72
	s_nop 0
	global_load_lds_dwordx4 v[160:161], off
	s_waitcnt vmcnt(8)
	s_waitcnt lgkmcnt(0)
	s_barrier
	v_mfma_i32_16x16x64_i8 v[94:97], v[156:159], v[214:217], v[94:97]
	v_mfma_i32_16x16x64_i8 v[90:93], v[190:193], v[214:217], v[90:93]
	v_mfma_i32_16x16x64_i8 v[86:89], v[156:159], v[226:229], v[86:89]
	v_mfma_i32_16x16x64_i8 v[82:85], v[190:193], v[226:229], v[82:85]
	v_mfma_i32_16x16x64_i8 v[78:81], v[156:159], v[234:237], v[78:81]
	v_mfma_i32_16x16x64_i8 v[74:77], v[190:193], v[234:237], v[74:77]
	v_mfma_i32_16x16x64_i8 v[70:73], v[156:159], v[242:245], v[70:73]
	v_mfma_i32_16x16x64_i8 v[66:69], v[190:193], v[242:245], v[66:69]
	v_mfma_i32_16x16x64_i8 v[94:97], v[172:175], v[222:225], v[94:97]
	v_mfma_i32_16x16x64_i8 v[90:93], v[194:197], v[222:225], v[90:93]
	v_mfma_i32_16x16x64_i8 v[86:89], v[172:175], v[230:233], v[86:89]
	v_mfma_i32_16x16x64_i8 v[82:85], v[194:197], v[230:233], v[82:85]
	v_mfma_i32_16x16x64_i8 v[78:81], v[172:175], v[238:241], v[78:81]
	v_mfma_i32_16x16x64_i8 v[74:77], v[194:197], v[238:241], v[74:77]
	v_mfma_i32_16x16x64_i8 v[70:73], v[172:175], v[246:249], v[70:73]
	v_mfma_i32_16x16x64_i8 v[66:69], v[194:197], v[246:249], v[66:69]
	v_mfma_i32_16x16x64_i8 v[30:33], v[198:201], v[214:217], v[30:33]
	v_mfma_i32_16x16x64_i8 v[26:29], v[206:209], v[214:217], v[26:29]
	v_mfma_i32_16x16x64_i8 v[22:25], v[198:201], v[226:229], v[22:25]
	v_mfma_i32_16x16x64_i8 v[18:21], v[206:209], v[226:229], v[18:21]
	v_mfma_i32_16x16x64_i8 v[14:17], v[198:201], v[234:237], v[14:17]
	v_mfma_i32_16x16x64_i8 v[10:13], v[206:209], v[234:237], v[10:13]
	v_mfma_i32_16x16x64_i8 v[6:9], v[198:201], v[242:245], v[6:9]
	v_mfma_i32_16x16x64_i8 v[2:5], v[206:209], v[242:245], v[2:5]
	v_mfma_i32_16x16x64_i8 v[30:33], v[202:205], v[222:225], v[30:33]
	v_mfma_i32_16x16x64_i8 v[26:29], v[210:213], v[222:225], v[26:29]
	v_mfma_i32_16x16x64_i8 v[22:25], v[202:205], v[230:233], v[22:25]
	v_mfma_i32_16x16x64_i8 v[18:21], v[210:213], v[230:233], v[18:21]
	v_mfma_i32_16x16x64_i8 v[14:17], v[202:205], v[238:241], v[14:17]
	v_mfma_i32_16x16x64_i8 v[10:13], v[210:213], v[238:241], v[10:13]
	v_mfma_i32_16x16x64_i8 v[6:9], v[202:205], v[246:249], v[6:9]
	v_mfma_i32_16x16x64_i8 v[2:5], v[210:213], v[246:249], v[2:5]
	s_barrier
	s_add_i32 s60, s60, 2
	s_add_u32 s15, s15, 0x100
	s_addc_u32 s17, s17, 0
	s_add_u32 s26, s26, 0x100
	s_addc_u32 s27, s27, 0
	s_cmp_gt_u32 s60, 13
	s_cbranch_scc0 .LBB0_696
	s_and_b64 vcc, exec, s[12:13]
	s_cbranch_vccz .LBB0_699
	s_barrier

.LBB0_702:
	s_mov_b32 s101, 1
	s_andn2_b64 vcc, exec, s[10:11]
	s_cbranch_vccnz .LBB0_684
	s_barrier
	s_branch .LBB0_684

.LBB0_1194:
	s_mov_b32 s101, 0
	s_add_u32 s10, s6, 0x44000000
	s_addc_u32 s11, s7, 0
	s_add_u32 s16, s6, 0x100000
	s_addc_u32 s17, s7, 0
	s_lshl_b64 s[12:13], s[54:55], 3
	s_add_u32 s12, s16, s12
	s_addc_u32 s13, s17, s13
	s_add_u32 s14, s6, 0x69000000
	s_addc_u32 s15, s7, 0
	v_readlane_b32 s6, v255, 28
	v_bfe_u32 v18, v10, 4, 2
	v_readlane_b32 s7, v255, 29
	s_add_u32 s16, s16, s6
	v_and_b32_e32 v17, 15, v10
	v_lshlrev_b32_e32 v19, 4, v18
	v_lshlrev_b32_e32 v10, 2, v10
	s_addc_u32 s17, s17, s7
	v_lshl_or_b32 v200, s4, 6, v17
	v_lshl_or_b32 v17, v17, 6, v19
	s_lshl_b32 s4, s4, 13
	v_and_b32_e32 v10, 32, v10
	v_bitop3_b32 v19, v17, s4, v10 bitop3:0xde
	s_lshl_b32 s4, s5, 5
	s_and_b32 s6, s4, 0x60
	s_add_i32 m0, s66, 0x18000
	v_lshl_add_u64 v[8:9], v[8:9], 0, s[44:45]
	s_lshl_b32 s4, s6, 7
	s_waitcnt vmcnt(2)
	s_barrier
	global_load_lds_dwordx4 v[8:9], off
	v_lshl_add_u64 v[6:7], v[6:7], 0, s[44:45]
	s_add_i32 m0, s66, 0x1a000
	s_add_i32 s70, s66, 0x8000
	s_add_i32 s71, s66, 0xa000
	v_bitop3_b32 v201, v17, s4, v10 bitop3:0xde
	global_load_lds_dwordx4 v[6:7], off
	v_lshl_add_u64 v[2:3], v[2:3], 0, s[44:45]
	s_mov_b32 m0, s70
	s_add_u32 s4, s58, 0x80080
	global_load_lds_dwordx4 v[2:3], off
	v_lshl_add_u64 v[2:3], v[4:5], 0, s[44:45]
	s_mov_b32 m0, s71
	s_addc_u32 s5, s59, 0
	global_load_lds_dwordx4 v[2:3], off
	s_add_i32 m0, s66, 0x1c000
	v_lshl_add_u64 v[2:3], s[4:5], 0, v[162:163]
	global_load_lds_dwordx4 v[2:3], off
	v_lshl_add_u64 v[2:3], s[4:5], 0, v[158:159]
	s_add_i32 m0, s66, 0x1e000
	s_and_b32 s73, s2, 7
	global_load_lds_dwordx4 v[2:3], off
	v_lshlrev_b32_e32 v2, 15, v14
	v_and_b32_e32 v2, 0xffff0000, v2
	v_lshl_add_u32 v2, v15, 12, v2
	v_and_b32_e32 v3, 1, v14
	v_lshl_or_b32 v2, v3, 6, v2
	s_ashr_i32 s74, s2, 3
	v_lshl_add_u32 v160, v16, 1, v2
	v_lshlrev_b32_e32 v2, 15, v11
	s_lshl_b32 s4, s73, 3
	s_and_b32 s5, s74, 7
	v_and_b32_e32 v2, 0xffff0000, v2
	s_waitcnt vmcnt(6)
	s_ashr_i32 s72, s2, 31
	s_or_b32 s75, s4, s5
	v_lshl_add_u32 v2, v12, 12, v2
	v_and_b32_e32 v3, 1, v11
	s_cmpk_lt_u32 s18, 0x100
	v_lshl_or_b32 v2, v3, 6, v2
	s_cselect_b64 s[18:19], -1, 0
	s_mov_b32 s76, 0
	v_cmp_eq_u32_e64 s[4:5], 0, v18
	v_lshl_or_b32 v202, v18, 3, s6
	v_mov_b32_e32 v161, v163
	v_lshl_add_u32 v172, v13, 1, v2
	v_mov_b32_e32 v173, v163
	v_add_u32_e32 v203, 0, v19
	s_barrier
	s_branch .LBB0_1197

.LBB0_1211:
	s_add_u32 s36, s56, 0xfff80080
	s_addc_u32 s37, s57, -1
	s_add_i32 s38, 0, 0x10000
	s_cmp_eq_u32 s78, 28
	s_cselect_b32 s61, s21, s37
	s_cselect_b32 s60, s20, s36
	s_cselect_b32 s59, s23, s62
	s_cselect_b32 s58, s22, s25
	s_add_i32 s39, 0, 0x14000
	v_add_u32_e32 v142, s38, v201
	v_add_u32_e32 v168, s39, v201
	ds_read_b128 v[110:113], v142
	ds_read_b128 v[118:121], v142 offset:1024
	ds_read_b128 v[138:141], v142 offset:2048
	ds_read_b128 v[142:145], v142 offset:3072
	ds_read_b128 v[146:149], v168
	ds_read_b128 v[150:153], v168 offset:1024
	ds_read_b128 v[174:177], v168 offset:2048
	ds_read_b128 v[178:181], v168 offset:3072
	v_lshl_add_u64 v[168:169], s[56:57], 0, v[172:173]
	s_add_i32 m0, s66, 0xc000
	ds_read_b128 v[182:185], v203
	ds_read_b128 v[186:189], v203 offset:1024
	ds_read_b128 v[190:193], v203 offset:2048
	ds_read_b128 v[194:197], v203 offset:3072
	ds_read_b128 v[204:207], v203 offset:4096
	ds_read_b128 v[208:211], v203 offset:5120
	ds_read_b128 v[212:215], v203 offset:6144
	ds_read_b128 v[222:225], v203 offset:7168
	global_load_lds_dwordx4 v[168:169], off
	v_lshl_add_u64 v[168:169], s[56:57], 0, v[160:161]
	s_add_i32 m0, s66, 0xe000
	s_nop 0
	global_load_lds_dwordx4 v[168:169], off
	s_waitcnt vmcnt(63)
	s_cmp_eq_i32 s78, -2
	s_cselect_b32 s100, s101, 0
	s_cmp_lg_u32 s100, 0
	s_cbranch_scc1 .Lrw_skip1211_0
	s_waitcnt vmcnt(8)
.Lrw_skip1211_0:
	s_waitcnt lgkmcnt(0)
	s_barrier
	v_mfma_f32_16x16x32_bf16 v[134:137], v[110:113], v[182:185], v[134:137]
	v_mfma_f32_16x16x32_bf16 v[130:133], v[138:141], v[182:185], v[130:133]
	v_mfma_f32_16x16x32_bf16 v[114:117], v[110:113], v[190:193], v[114:117]
	v_mfma_f32_16x16x32_bf16 v[106:109], v[138:141], v[190:193], v[106:109]
	v_mfma_f32_16x16x32_bf16 v[94:97], v[110:113], v[204:207], v[94:97]
	v_mfma_f32_16x16x32_bf16 v[90:93], v[138:141], v[204:207], v[90:93]
	v_mfma_f32_16x16x32_bf16 v[78:81], v[110:113], v[212:215], v[78:81]
	v_mfma_f32_16x16x32_bf16 v[74:77], v[138:141], v[212:215], v[74:77]
	v_mfma_f32_16x16x32_bf16 v[134:137], v[118:121], v[186:189], v[134:137]
	v_mfma_f32_16x16x32_bf16 v[130:133], v[142:145], v[186:189], v[130:133]
	v_mfma_f32_16x16x32_bf16 v[114:117], v[118:121], v[194:197], v[114:117]
	v_mfma_f32_16x16x32_bf16 v[106:109], v[142:145], v[194:197], v[106:109]
	v_mfma_f32_16x16x32_bf16 v[94:97], v[118:121], v[208:211], v[94:97]
	v_mfma_f32_16x16x32_bf16 v[90:93], v[142:145], v[208:211], v[90:93]
	v_mfma_f32_16x16x32_bf16 v[78:81], v[118:121], v[222:225], v[78:81]
	v_mfma_f32_16x16x32_bf16 v[74:77], v[142:145], v[222:225], v[74:77]
	v_mfma_f32_16x16x32_bf16 v[126:129], v[146:149], v[182:185], v[126:129]
	v_mfma_f32_16x16x32_bf16 v[122:125], v[174:177], v[182:185], v[122:125]
	v_mfma_f32_16x16x32_bf16 v[102:105], v[146:149], v[190:193], v[102:105]
	v_mfma_f32_16x16x32_bf16 v[98:101], v[174:177], v[190:193], v[98:101]
	v_mfma_f32_16x16x32_bf16 v[86:89], v[146:149], v[204:207], v[86:89]
	v_mfma_f32_16x16x32_bf16 v[82:85], v[174:177], v[204:207], v[82:85]
	v_mfma_f32_16x16x32_bf16 v[70:73], v[146:149], v[212:215], v[70:73]
	v_mfma_f32_16x16x32_bf16 v[66:69], v[174:177], v[212:215], v[66:69]
	v_mfma_f32_16x16x32_bf16 v[126:129], v[150:153], v[186:189], v[126:129]
	v_mfma_f32_16x16x32_bf16 v[122:125], v[178:181], v[186:189], v[122:125]
	v_mfma_f32_16x16x32_bf16 v[102:105], v[150:153], v[194:197], v[102:105]
	v_mfma_f32_16x16x32_bf16 v[98:101], v[178:181], v[194:197], v[98:101]
	v_mfma_f32_16x16x32_bf16 v[86:89], v[150:153], v[208:211], v[86:89]
	v_mfma_f32_16x16x32_bf16 v[82:85], v[178:181], v[208:211], v[82:85]
	v_mfma_f32_16x16x32_bf16 v[70:73], v[150:153], v[222:225], v[70:73]
	v_mfma_f32_16x16x32_bf16 v[66:69], v[178:181], v[222:225], v[66:69]
	s_barrier
	s_add_i32 s36, s38, s27
	v_lshl_add_u64 v[168:169], s[58:59], 0, v[162:163]
	s_mov_b32 m0, s36
	ds_read_b128 v[182:185], v203 offset:16384
	ds_read_b128 v[186:189], v203 offset:17408
	ds_read_b128 v[190:193], v203 offset:18432
	ds_read_b128 v[194:197], v203 offset:19456
	ds_read_b128 v[204:207], v203 offset:20480
	ds_read_b128 v[208:211], v203 offset:21504
	ds_read_b128 v[212:215], v203 offset:22528
	ds_read_b128 v[222:225], v203 offset:23552
	global_load_lds_dwordx4 v[168:169], off
	s_add_i32 m0, s36, 0x2000
	s_add_u32 s36, s58, 0x80000
	v_lshl_add_u64 v[170:171], s[58:59], 0, v[158:159]
	s_addc_u32 s37, s59, 0
	s_add_i32 s38, s39, s27
	global_load_lds_dwordx4 v[170:171], off
	v_lshl_add_u64 v[198:199], s[36:37], 0, v[162:163]
	s_mov_b32 m0, s38
	v_lshl_add_u64 v[216:217], s[60:61], 0, v[156:157]
	global_load_lds_dwordx4 v[198:199], off
	v_lshl_add_u64 v[198:199], s[36:37], 0, v[158:159]
	s_add_i32 m0, s38, 0x2000
	s_nop 0
	global_load_lds_dwordx4 v[198:199], off
	v_lshl_add_u64 v[198:199], s[60:61], 0, v[154:155]
	s_mov_b32 m0, s66
	s_nop 0
	global_load_lds_dwordx4 v[198:199], off
	s_mov_b32 m0, s67
	s_nop 0
	global_load_lds_dwordx4 v[216:217], off
	s_waitcnt vmcnt(63)
	s_cmp_eq_i32 s78, -2
	s_cselect_b32 s100, s101, 0
	s_cmp_lg_u32 s100, 0
	s_cbranch_scc1 .Lrw_skip1211_1
	s_waitcnt vmcnt(8)
.Lrw_skip1211_1:
	s_waitcnt lgkmcnt(0)
	s_barrier
	v_mfma_f32_16x16x32_bf16 v[62:65], v[110:113], v[182:185], v[62:65]
	v_mfma_f32_16x16x32_bf16 v[58:61], v[138:141], v[182:185], v[58:61]
	v_mfma_f32_16x16x32_bf16 v[46:49], v[110:113], v[190:193], v[46:49]
	v_mfma_f32_16x16x32_bf16 v[42:45], v[138:141], v[190:193], v[42:45]
	v_mfma_f32_16x16x32_bf16 v[30:33], v[110:113], v[204:207], v[30:33]
	v_mfma_f32_16x16x32_bf16 v[26:29], v[138:141], v[204:207], v[26:29]
	v_mfma_f32_16x16x32_bf16 v[14:17], v[110:113], v[212:215], v[14:17]
	v_mfma_f32_16x16x32_bf16 v[10:13], v[138:141], v[212:215], v[10:13]
	v_mfma_f32_16x16x32_bf16 v[62:65], v[118:121], v[186:189], v[62:65]
	v_mfma_f32_16x16x32_bf16 v[58:61], v[142:145], v[186:189], v[58:61]
	v_mfma_f32_16x16x32_bf16 v[46:49], v[118:121], v[194:197], v[46:49]
	v_mfma_f32_16x16x32_bf16 v[42:45], v[142:145], v[194:197], v[42:45]
	v_mfma_f32_16x16x32_bf16 v[30:33], v[118:121], v[208:211], v[30:33]
	v_mfma_f32_16x16x32_bf16 v[26:29], v[142:145], v[208:211], v[26:29]
	v_mfma_f32_16x16x32_bf16 v[14:17], v[118:121], v[222:225], v[14:17]
	v_mfma_f32_16x16x32_bf16 v[10:13], v[142:145], v[222:225], v[10:13]
	v_mfma_f32_16x16x32_bf16 v[54:57], v[146:149], v[182:185], v[54:57]
	v_mfma_f32_16x16x32_bf16 v[50:53], v[174:177], v[182:185], v[50:53]
	v_mfma_f32_16x16x32_bf16 v[38:41], v[146:149], v[190:193], v[38:41]
	v_mfma_f32_16x16x32_bf16 v[34:37], v[174:177], v[190:193], v[34:37]
	v_mfma_f32_16x16x32_bf16 v[22:25], v[146:149], v[204:207], v[22:25]
	v_mfma_f32_16x16x32_bf16 v[18:21], v[174:177], v[204:207], v[18:21]
	v_mfma_f32_16x16x32_bf16 v[6:9], v[146:149], v[212:215], v[6:9]
	v_mfma_f32_16x16x32_bf16 v[2:5], v[174:177], v[212:215], v[2:5]
	v_mfma_f32_16x16x32_bf16 v[54:57], v[150:153], v[186:189], v[54:57]
	v_mfma_f32_16x16x32_bf16 v[50:53], v[178:181], v[186:189], v[50:53]
	v_mfma_f32_16x16x32_bf16 v[38:41], v[150:153], v[194:197], v[38:41]
	v_mfma_f32_16x16x32_bf16 v[34:37], v[178:181], v[194:197], v[34:37]
	v_mfma_f32_16x16x32_bf16 v[22:25], v[150:153], v[208:211], v[22:25]
	v_mfma_f32_16x16x32_bf16 v[18:21], v[178:181], v[208:211], v[18:21]
	v_mfma_f32_16x16x32_bf16 v[6:9], v[150:153], v[222:225], v[6:9]
	v_mfma_f32_16x16x32_bf16 v[2:5], v[178:181], v[222:225], v[2:5]
	s_barrier
	s_add_i32 s38, 0, 0x18000
	s_add_i32 s39, 0, 0x1c000
	v_add_u32_e32 v142, s38, v201
	v_add_u32_e32 v178, s39, v201
	ds_read_b128 v[110:113], v142
	ds_read_b128 v[118:121], v142 offset:1024
	ds_read_b128 v[138:141], v142 offset:2048
	ds_read_b128 v[142:145], v142 offset:3072
	ds_read_b128 v[146:149], v178
	ds_read_b128 v[150:153], v178 offset:1024
	ds_read_b128 v[174:177], v178 offset:2048
	ds_read_b128 v[178:181], v178 offset:3072
	s_add_u32 s36, s60, 0x80000
	s_addc_u32 s37, s61, 0
	s_mov_b32 m0, s68
	v_lshl_add_u64 v[226:227], s[36:37], 0, v[154:155]
	ds_read_b128 v[182:185], v203 offset:32768
	ds_read_b128 v[186:189], v203 offset:33792
	ds_read_b128 v[190:193], v203 offset:34816
	ds_read_b128 v[194:197], v203 offset:35840
	ds_read_b128 v[204:207], v203 offset:36864
	ds_read_b128 v[208:211], v203 offset:37888
	ds_read_b128 v[212:215], v203 offset:38912
	ds_read_b128 v[222:225], v203 offset:39936
	global_load_lds_dwordx4 v[226:227], off
	v_lshl_add_u64 v[226:227], s[36:37], 0, v[156:157]
	s_mov_b32 m0, s69
	s_nop 0
	global_load_lds_dwordx4 v[226:227], off
	s_waitcnt vmcnt(8)
	s_waitcnt lgkmcnt(0)
	s_barrier
	v_mfma_f32_16x16x32_bf16 v[134:137], v[110:113], v[182:185], v[134:137]
	v_mfma_f32_16x16x32_bf16 v[130:133], v[138:141], v[182:185], v[130:133]
	v_mfma_f32_16x16x32_bf16 v[114:117], v[110:113], v[190:193], v[114:117]
	v_mfma_f32_16x16x32_bf16 v[106:109], v[138:141], v[190:193], v[106:109]
	v_mfma_f32_16x16x32_bf16 v[94:97], v[110:113], v[204:207], v[94:97]
	v_mfma_f32_16x16x32_bf16 v[90:93], v[138:141], v[204:207], v[90:93]
	v_mfma_f32_16x16x32_bf16 v[78:81], v[110:113], v[212:215], v[78:81]
	v_mfma_f32_16x16x32_bf16 v[74:77], v[138:141], v[212:215], v[74:77]
	v_mfma_f32_16x16x32_bf16 v[134:137], v[118:121], v[186:189], v[134:137]
	v_mfma_f32_16x16x32_bf16 v[130:133], v[142:145], v[186:189], v[130:133]
	v_mfma_f32_16x16x32_bf16 v[114:117], v[118:121], v[194:197], v[114:117]
	v_mfma_f32_16x16x32_bf16 v[106:109], v[142:145], v[194:197], v[106:109]
	v_mfma_f32_16x16x32_bf16 v[94:97], v[118:121], v[208:211], v[94:97]
	v_mfma_f32_16x16x32_bf16 v[90:93], v[142:145], v[208:211], v[90:93]
	v_mfma_f32_16x16x32_bf16 v[78:81], v[118:121], v[222:225], v[78:81]
	v_mfma_f32_16x16x32_bf16 v[74:77], v[142:145], v[222:225], v[74:77]
	v_mfma_f32_16x16x32_bf16 v[126:129], v[146:149], v[182:185], v[126:129]
	v_mfma_f32_16x16x32_bf16 v[122:125], v[174:177], v[182:185], v[122:125]
	v_mfma_f32_16x16x32_bf16 v[102:105], v[146:149], v[190:193], v[102:105]
	v_mfma_f32_16x16x32_bf16 v[98:101], v[174:177], v[190:193], v[98:101]
	v_mfma_f32_16x16x32_bf16 v[86:89], v[146:149], v[204:207], v[86:89]
	v_mfma_f32_16x16x32_bf16 v[82:85], v[174:177], v[204:207], v[82:85]
	v_mfma_f32_16x16x32_bf16 v[70:73], v[146:149], v[212:215], v[70:73]
	v_mfma_f32_16x16x32_bf16 v[66:69], v[174:177], v[212:215], v[66:69]
	v_mfma_f32_16x16x32_bf16 v[126:129], v[150:153], v[186:189], v[126:129]
	v_mfma_f32_16x16x32_bf16 v[122:125], v[178:181], v[186:189], v[122:125]
	v_mfma_f32_16x16x32_bf16 v[102:105], v[150:153], v[194:197], v[102:105]
	v_mfma_f32_16x16x32_bf16 v[98:101], v[178:181], v[194:197], v[98:101]
	v_mfma_f32_16x16x32_bf16 v[86:89], v[150:153], v[208:211], v[86:89]
	v_mfma_f32_16x16x32_bf16 v[82:85], v[178:181], v[208:211], v[82:85]
	v_mfma_f32_16x16x32_bf16 v[70:73], v[150:153], v[222:225], v[70:73]
	v_mfma_f32_16x16x32_bf16 v[66:69], v[178:181], v[222:225], v[66:69]
	s_barrier
	s_add_i32 s36, s38, s27
	v_lshl_add_u64 v[168:169], v[168:169], 0, s[44:45]
	s_mov_b32 m0, s36
	ds_read_b128 v[182:185], v203 offset:49152
	ds_read_b128 v[186:189], v203 offset:50176
	ds_read_b128 v[190:193], v203 offset:51200
	ds_read_b128 v[194:197], v203 offset:52224
	ds_read_b128 v[204:207], v203 offset:53248
	ds_read_b128 v[208:211], v203 offset:54272
	ds_read_b128 v[212:215], v203 offset:55296
	ds_read_b128 v[222:225], v203 offset:56320
	global_load_lds_dwordx4 v[168:169], off
	s_add_i32 m0, s36, 0x2000
	s_add_u32 s36, s58, 0x80080
	v_lshl_add_u64 v[168:169], v[170:171], 0, s[44:45]
	s_addc_u32 s37, s59, 0
	s_add_i32 s38, s39, s27
	global_load_lds_dwordx4 v[168:169], off
	v_lshl_add_u64 v[168:169], s[36:37], 0, v[162:163]
	s_mov_b32 m0, s38
	s_nop 0
	global_load_lds_dwordx4 v[168:169], off
	v_lshl_add_u64 v[168:169], s[36:37], 0, v[158:159]
	s_add_i32 m0, s38, 0x2000
	s_nop 0
	global_load_lds_dwordx4 v[168:169], off
	v_lshl_add_u64 v[168:169], v[198:199], 0, s[44:45]
	s_mov_b32 m0, s70
	s_nop 0
	global_load_lds_dwordx4 v[168:169], off
	v_lshl_add_u64 v[168:169], v[216:217], 0, s[44:45]
	s_mov_b32 m0, s71
	s_nop 0
	global_load_lds_dwordx4 v[168:169], off
	s_waitcnt vmcnt(8)
	s_waitcnt lgkmcnt(0)
	s_barrier
	v_mfma_f32_16x16x32_bf16 v[62:65], v[110:113], v[182:185], v[62:65]
	v_mfma_f32_16x16x32_bf16 v[58:61], v[138:141], v[182:185], v[58:61]
	v_mfma_f32_16x16x32_bf16 v[46:49], v[110:113], v[190:193], v[46:49]
	v_mfma_f32_16x16x32_bf16 v[42:45], v[138:141], v[190:193], v[42:45]
	v_mfma_f32_16x16x32_bf16 v[30:33], v[110:113], v[204:207], v[30:33]
	v_mfma_f32_16x16x32_bf16 v[26:29], v[138:141], v[204:207], v[26:29]
	v_mfma_f32_16x16x32_bf16 v[14:17], v[110:113], v[212:215], v[14:17]
	v_mfma_f32_16x16x32_bf16 v[10:13], v[138:141], v[212:215], v[10:13]
	v_mfma_f32_16x16x32_bf16 v[62:65], v[118:121], v[186:189], v[62:65]
	v_mfma_f32_16x16x32_bf16 v[58:61], v[142:145], v[186:189], v[58:61]
	v_mfma_f32_16x16x32_bf16 v[46:49], v[118:121], v[194:197], v[46:49]
	v_mfma_f32_16x16x32_bf16 v[42:45], v[142:145], v[194:197], v[42:45]
	v_mfma_f32_16x16x32_bf16 v[30:33], v[118:121], v[208:211], v[30:33]
	v_mfma_f32_16x16x32_bf16 v[26:29], v[142:145], v[208:211], v[26:29]
	v_mfma_f32_16x16x32_bf16 v[14:17], v[118:121], v[222:225], v[14:17]
	v_mfma_f32_16x16x32_bf16 v[10:13], v[142:145], v[222:225], v[10:13]
	v_mfma_f32_16x16x32_bf16 v[54:57], v[146:149], v[182:185], v[54:57]
	v_mfma_f32_16x16x32_bf16 v[50:53], v[174:177], v[182:185], v[50:53]
	v_mfma_f32_16x16x32_bf16 v[38:41], v[146:149], v[190:193], v[38:41]
	v_mfma_f32_16x16x32_bf16 v[34:37], v[174:177], v[190:193], v[34:37]
	v_mfma_f32_16x16x32_bf16 v[22:25], v[146:149], v[204:207], v[22:25]
	v_mfma_f32_16x16x32_bf16 v[18:21], v[174:177], v[204:207], v[18:21]
	v_mfma_f32_16x16x32_bf16 v[6:9], v[146:149], v[212:215], v[6:9]
	v_mfma_f32_16x16x32_bf16 v[2:5], v[174:177], v[212:215], v[2:5]
	v_mfma_f32_16x16x32_bf16 v[54:57], v[150:153], v[186:189], v[54:57]
	v_mfma_f32_16x16x32_bf16 v[50:53], v[178:181], v[186:189], v[50:53]
	v_mfma_f32_16x16x32_bf16 v[38:41], v[150:153], v[194:197], v[38:41]
	v_mfma_f32_16x16x32_bf16 v[34:37], v[178:181], v[194:197], v[34:37]
	v_mfma_f32_16x16x32_bf16 v[22:25], v[150:153], v[208:211], v[22:25]
	v_mfma_f32_16x16x32_bf16 v[18:21], v[178:181], v[208:211], v[18:21]
	v_mfma_f32_16x16x32_bf16 v[6:9], v[150:153], v[222:225], v[6:9]
	v_mfma_f32_16x16x32_bf16 v[2:5], v[178:181], v[222:225], v[2:5]
	s_barrier
	s_add_i32 s78, s78, 2
	s_add_u32 s25, s25, 0x100
	s_addc_u32 s62, s62, 0
	s_add_u32 s56, s56, 0x100
	s_addc_u32 s57, s57, 0
	s_cmp_gt_u32 s78, 29
	s_cbranch_scc0 .LBB0_1211
	s_and_b64 vcc, exec, s[18:19]
	s_cbranch_vccz .LBB0_1214
	s_barrier

.LBB0_1430:
	s_mov_b32 s101, 0
	s_add_u32 s12, s6, 0x44000000
	s_addc_u32 s13, s7, 0
	v_readlane_b32 s8, v255, 25
	s_add_u32 s18, s6, 0x100000
	v_readlane_b32 s9, v255, 26
	s_addc_u32 s19, s7, 0
	s_lshl_b64 s[8:9], s[8:9], 3
	s_add_u32 s14, s18, s8
	s_addc_u32 s15, s19, s9
	s_add_u32 s16, s6, 0x67000000
	s_addc_u32 s17, s7, 0
	s_lshl_b64 s[6:7], s[54:55], 3
	v_bfe_u32 v14, v6, 4, 2
	s_add_u32 s18, s18, s6
	v_and_b32_e32 v13, 15, v6
	v_lshlrev_b32_e32 v15, 4, v14
	v_lshlrev_b32_e32 v6, 2, v6
	s_addc_u32 s19, s19, s7
	v_lshl_or_b32 v200, s4, 6, v13
	v_lshl_or_b32 v13, v13, 6, v15
	s_lshl_b32 s4, s4, 13
	v_and_b32_e32 v6, 32, v6
	v_bitop3_b32 v15, v13, s4, v6 bitop3:0xde
	s_lshl_b32 s4, s5, 5
	s_and_b32 s6, s4, 0x60
	s_add_i32 m0, s65, 0x18000
	v_lshl_add_u64 v[2:3], v[2:3], 0, s[44:45]
	s_lshl_b32 s4, s6, 7
	s_waitcnt vmcnt(2)
	s_barrier
	global_load_lds_dwordx4 v[2:3], off
	s_add_i32 m0, s65, 0x1a000
	v_bitop3_b32 v201, v13, s4, v6 bitop3:0xde
	s_add_u32 s4, s26, 0x8000
	v_mov_b32_e32 v155, v163
	v_lshl_add_u64 v[2:3], v[4:5], 0, s[44:45]
	s_addc_u32 s5, s27, 0
	s_add_i32 s69, s65, 0x8000
	v_mov_b32_e32 v157, v163
	global_load_lds_dwordx4 v[2:3], off
	v_lshl_add_u64 v[2:3], s[4:5], 0, v[154:155]
	s_mov_b32 m0, s69
	s_add_i32 s70, s65, 0xa000
	global_load_lds_dwordx4 v[2:3], off
	v_lshl_add_u64 v[2:3], s[4:5], 0, v[156:157]
	s_add_u32 s4, s56, 0x160080
	s_mov_b32 m0, s70
	s_addc_u32 s5, s57, 0
	global_load_lds_dwordx4 v[2:3], off
	s_add_i32 m0, s65, 0x1c000
	v_lshl_add_u64 v[2:3], s[4:5], 0, v[162:163]
	global_load_lds_dwordx4 v[2:3], off
	v_lshl_add_u64 v[2:3], s[4:5], 0, v[158:159]
	s_add_i32 m0, s65, 0x1e000
	s_and_b32 s72, s2, 7
	global_load_lds_dwordx4 v[2:3], off
	v_lshlrev_b32_e32 v2, 10, v10
	v_and_b32_e32 v2, 0xfffff800, v2
	v_lshl_add_u32 v2, v11, 7, v2
	v_and_b32_e32 v3, 1, v10
	v_lshl_or_b32 v2, v3, 6, v2
	v_lshl_add_u32 v160, v12, 1, v2
	v_lshlrev_b32_e32 v2, 10, v7
	s_lshl_b32 s4, s72, 3
	s_ashr_i32 s73, s2, 6
	s_bfe_u32 s75, s2, 0x30003
	v_and_b32_e32 v2, 0xfffff800, v2
	s_waitcnt vmcnt(6)
	s_ashr_i32 s71, s2, 31
	s_add_i32 s74, s4, s73
	s_or_b32 s76, s4, s75
	v_lshl_add_u32 v2, v8, 7, v2
	v_and_b32_e32 v3, 1, v7
	s_cmpk_lt_u32 s20, 0x100
	v_lshl_or_b32 v2, v3, 6, v2
	s_cselect_b64 s[20:21], -1, 0
	s_mov_b32 s77, 0
	v_cmp_eq_u32_e64 s[4:5], 0, v14
	v_lshl_or_b32 v202, v14, 3, s6
	v_mov_b32_e32 v161, v163
	v_lshl_add_u32 v172, v9, 1, v2
	v_mov_b32_e32 v173, v163
	v_add_u32_e32 v203, 0, v15
	s_barrier
	s_branch .LBB0_1433

.LBB0_1446:
	s_add_u32 s8, s26, 0x4000
	s_addc_u32 s9, s27, 0
	s_cmpk_eq_i32 s84, 0x54
	s_cselect_b32 s60, s22, s8
	s_cselect_b32 s61, s23, s9
	s_cselect_b32 s58, s24, s82
	s_cselect_b32 s59, s25, s83
	s_add_u32 s56, s60, 0x8000
	s_addc_u32 s57, s61, 0
	s_add_i32 s8, 0, 0x10000
	s_add_i32 s36, 0, 0x14000
	v_add_u32_e32 v142, s8, v201
	v_add_u32_e32 v168, s36, v201
	ds_read_b128 v[110:113], v142
	ds_read_b128 v[118:121], v142 offset:1024
	ds_read_b128 v[138:141], v142 offset:2048
	ds_read_b128 v[142:145], v142 offset:3072
	ds_read_b128 v[146:149], v168
	ds_read_b128 v[150:153], v168 offset:1024
	ds_read_b128 v[174:177], v168 offset:2048
	ds_read_b128 v[178:181], v168 offset:3072
	v_lshl_add_u64 v[168:169], s[26:27], 0, v[172:173]
	s_add_i32 m0, s65, 0xc000
	ds_read_b128 v[182:185], v203
	ds_read_b128 v[186:189], v203 offset:1024
	ds_read_b128 v[190:193], v203 offset:2048
	ds_read_b128 v[194:197], v203 offset:3072
	ds_read_b128 v[204:207], v203 offset:4096
	ds_read_b128 v[208:211], v203 offset:5120
	ds_read_b128 v[212:215], v203 offset:6144
	ds_read_b128 v[222:225], v203 offset:7168
	global_load_lds_dwordx4 v[168:169], off
	v_lshl_add_u64 v[168:169], s[26:27], 0, v[160:161]
	s_add_i32 m0, s65, 0xe000
	s_nop 0
	global_load_lds_dwordx4 v[168:169], off
	s_waitcnt vmcnt(63)
	s_cmp_eq_i32 s84, -2
	s_cselect_b32 s100, s101, 0
	s_cmp_lg_u32 s100, 0
	s_cbranch_scc1 .Lrw_skip1446_0
	s_waitcnt vmcnt(8)
.Lrw_skip1446_0:
	s_waitcnt lgkmcnt(0)
	s_barrier
	v_mfma_f32_16x16x32_bf16 v[134:137], v[110:113], v[182:185], v[134:137]
	v_mfma_f32_16x16x32_bf16 v[130:133], v[138:141], v[182:185], v[130:133]
	v_mfma_f32_16x16x32_bf16 v[114:117], v[110:113], v[190:193], v[114:117]
	v_mfma_f32_16x16x32_bf16 v[106:109], v[138:141], v[190:193], v[106:109]
	v_mfma_f32_16x16x32_bf16 v[94:97], v[110:113], v[204:207], v[94:97]
	v_mfma_f32_16x16x32_bf16 v[90:93], v[138:141], v[204:207], v[90:93]
	v_mfma_f32_16x16x32_bf16 v[78:81], v[110:113], v[212:215], v[78:81]
	v_mfma_f32_16x16x32_bf16 v[74:77], v[138:141], v[212:215], v[74:77]
	v_mfma_f32_16x16x32_bf16 v[134:137], v[118:121], v[186:189], v[134:137]
	v_mfma_f32_16x16x32_bf16 v[130:133], v[142:145], v[186:189], v[130:133]
	v_mfma_f32_16x16x32_bf16 v[114:117], v[118:121], v[194:197], v[114:117]
	v_mfma_f32_16x16x32_bf16 v[106:109], v[142:145], v[194:197], v[106:109]
	v_mfma_f32_16x16x32_bf16 v[94:97], v[118:121], v[208:211], v[94:97]
	v_mfma_f32_16x16x32_bf16 v[90:93], v[142:145], v[208:211], v[90:93]
	v_mfma_f32_16x16x32_bf16 v[78:81], v[118:121], v[222:225], v[78:81]
	v_mfma_f32_16x16x32_bf16 v[74:77], v[142:145], v[222:225], v[74:77]
	v_mfma_f32_16x16x32_bf16 v[126:129], v[146:149], v[182:185], v[126:129]
	v_mfma_f32_16x16x32_bf16 v[122:125], v[174:177], v[182:185], v[122:125]
	v_mfma_f32_16x16x32_bf16 v[102:105], v[146:149], v[190:193], v[102:105]
	v_mfma_f32_16x16x32_bf16 v[98:101], v[174:177], v[190:193], v[98:101]
	v_mfma_f32_16x16x32_bf16 v[86:89], v[146:149], v[204:207], v[86:89]
	v_mfma_f32_16x16x32_bf16 v[82:85], v[174:177], v[204:207], v[82:85]
	v_mfma_f32_16x16x32_bf16 v[70:73], v[146:149], v[212:215], v[70:73]
	v_mfma_f32_16x16x32_bf16 v[66:69], v[174:177], v[212:215], v[66:69]
	v_mfma_f32_16x16x32_bf16 v[126:129], v[150:153], v[186:189], v[126:129]
	v_mfma_f32_16x16x32_bf16 v[122:125], v[178:181], v[186:189], v[122:125]
	v_mfma_f32_16x16x32_bf16 v[102:105], v[150:153], v[194:197], v[102:105]
	v_mfma_f32_16x16x32_bf16 v[98:101], v[178:181], v[194:197], v[98:101]
	v_mfma_f32_16x16x32_bf16 v[86:89], v[150:153], v[208:211], v[86:89]
	v_mfma_f32_16x16x32_bf16 v[82:85], v[178:181], v[208:211], v[82:85]
	v_mfma_f32_16x16x32_bf16 v[70:73], v[150:153], v[222:225], v[70:73]
	v_mfma_f32_16x16x32_bf16 v[66:69], v[178:181], v[222:225], v[66:69]
	s_barrier
	s_add_i32 s8, s8, s64
	v_lshl_add_u64 v[168:169], s[58:59], 0, v[162:163]
	s_mov_b32 m0, s8
	ds_read_b128 v[182:185], v203 offset:16384
	ds_read_b128 v[186:189], v203 offset:17408
	ds_read_b128 v[190:193], v203 offset:18432
	ds_read_b128 v[194:197], v203 offset:19456
	ds_read_b128 v[204:207], v203 offset:20480
	ds_read_b128 v[208:211], v203 offset:21504
	ds_read_b128 v[212:215], v203 offset:22528
	ds_read_b128 v[222:225], v203 offset:23552
	global_load_lds_dwordx4 v[168:169], off
	s_add_i32 m0, s8, 0x2000
	s_add_u32 s8, s58, 0x160000
	v_lshl_add_u64 v[170:171], s[58:59], 0, v[158:159]
	s_addc_u32 s9, s59, 0
	s_add_i32 s36, s36, s64
	global_load_lds_dwordx4 v[170:171], off
	v_lshl_add_u64 v[198:199], s[8:9], 0, v[162:163]
	s_mov_b32 m0, s36
	s_nop 0
	global_load_lds_dwordx4 v[198:199], off
	v_lshl_add_u64 v[198:199], s[8:9], 0, v[158:159]
	s_add_i32 m0, s36, 0x2000
	s_nop 0
	global_load_lds_dwordx4 v[198:199], off
	v_lshl_add_u64 v[198:199], s[60:61], 0, v[154:155]
	s_mov_b32 m0, s65
	s_nop 0
	global_load_lds_dwordx4 v[198:199], off
	v_lshl_add_u64 v[198:199], s[60:61], 0, v[156:157]
	s_mov_b32 m0, s66
	s_nop 0
	global_load_lds_dwordx4 v[198:199], off
	s_waitcnt vmcnt(63)
	s_cmp_eq_i32 s84, -2
	s_cselect_b32 s100, s101, 0
	s_cmp_lg_u32 s100, 0
	s_cbranch_scc1 .Lrw_skip1446_1
	s_waitcnt vmcnt(8)
.Lrw_skip1446_1:
	s_waitcnt lgkmcnt(0)
	s_barrier
	v_mfma_f32_16x16x32_bf16 v[62:65], v[110:113], v[182:185], v[62:65]
	v_mfma_f32_16x16x32_bf16 v[58:61], v[138:141], v[182:185], v[58:61]
	v_mfma_f32_16x16x32_bf16 v[46:49], v[110:113], v[190:193], v[46:49]
	v_mfma_f32_16x16x32_bf16 v[42:45], v[138:141], v[190:193], v[42:45]
	v_mfma_f32_16x16x32_bf16 v[30:33], v[110:113], v[204:207], v[30:33]
	v_mfma_f32_16x16x32_bf16 v[26:29], v[138:141], v[204:207], v[26:29]
	v_mfma_f32_16x16x32_bf16 v[14:17], v[110:113], v[212:215], v[14:17]
	v_mfma_f32_16x16x32_bf16 v[10:13], v[138:141], v[212:215], v[10:13]
	v_mfma_f32_16x16x32_bf16 v[62:65], v[118:121], v[186:189], v[62:65]
	v_mfma_f32_16x16x32_bf16 v[58:61], v[142:145], v[186:189], v[58:61]
	v_mfma_f32_16x16x32_bf16 v[46:49], v[118:121], v[194:197], v[46:49]
	v_mfma_f32_16x16x32_bf16 v[42:45], v[142:145], v[194:197], v[42:45]
	v_mfma_f32_16x16x32_bf16 v[30:33], v[118:121], v[208:211], v[30:33]
	v_mfma_f32_16x16x32_bf16 v[26:29], v[142:145], v[208:211], v[26:29]
	v_mfma_f32_16x16x32_bf16 v[14:17], v[118:121], v[222:225], v[14:17]
	v_mfma_f32_16x16x32_bf16 v[10:13], v[142:145], v[222:225], v[10:13]
	v_mfma_f32_16x16x32_bf16 v[54:57], v[146:149], v[182:185], v[54:57]
	v_mfma_f32_16x16x32_bf16 v[50:53], v[174:177], v[182:185], v[50:53]
	v_mfma_f32_16x16x32_bf16 v[38:41], v[146:149], v[190:193], v[38:41]
	v_mfma_f32_16x16x32_bf16 v[34:37], v[174:177], v[190:193], v[34:37]
	v_mfma_f32_16x16x32_bf16 v[22:25], v[146:149], v[204:207], v[22:25]
	v_mfma_f32_16x16x32_bf16 v[18:21], v[174:177], v[204:207], v[18:21]
	v_mfma_f32_16x16x32_bf16 v[6:9], v[146:149], v[212:215], v[6:9]
	v_mfma_f32_16x16x32_bf16 v[2:5], v[174:177], v[212:215], v[2:5]
	v_mfma_f32_16x16x32_bf16 v[54:57], v[150:153], v[186:189], v[54:57]
	v_mfma_f32_16x16x32_bf16 v[50:53], v[178:181], v[186:189], v[50:53]
	v_mfma_f32_16x16x32_bf16 v[38:41], v[150:153], v[194:197], v[38:41]
	v_mfma_f32_16x16x32_bf16 v[34:37], v[178:181], v[194:197], v[34:37]
	v_mfma_f32_16x16x32_bf16 v[22:25], v[150:153], v[208:211], v[22:25]
	v_mfma_f32_16x16x32_bf16 v[18:21], v[178:181], v[208:211], v[18:21]
	v_mfma_f32_16x16x32_bf16 v[6:9], v[150:153], v[222:225], v[6:9]
	v_mfma_f32_16x16x32_bf16 v[2:5], v[178:181], v[222:225], v[2:5]
	s_barrier
	s_add_i32 s36, 0, 0x18000
	s_add_i32 s37, 0, 0x1c000
	v_add_u32_e32 v142, s36, v201
	v_add_u32_e32 v178, s37, v201
	ds_read_b128 v[110:113], v142
	ds_read_b128 v[118:121], v142 offset:1024
	ds_read_b128 v[138:141], v142 offset:2048
	ds_read_b128 v[142:145], v142 offset:3072
	ds_read_b128 v[146:149], v178
	ds_read_b128 v[150:153], v178 offset:1024
	ds_read_b128 v[174:177], v178 offset:2048
	ds_read_b128 v[178:181], v178 offset:3072
	s_add_u32 s8, s60, 0x4000
	s_addc_u32 s9, s61, 0
	s_mov_b32 m0, s67
	v_lshl_add_u64 v[198:199], s[8:9], 0, v[154:155]
	ds_read_b128 v[182:185], v203 offset:32768
	ds_read_b128 v[186:189], v203 offset:33792
	ds_read_b128 v[190:193], v203 offset:34816
	ds_read_b128 v[194:197], v203 offset:35840
	ds_read_b128 v[204:207], v203 offset:36864
	ds_read_b128 v[208:211], v203 offset:37888
	ds_read_b128 v[212:215], v203 offset:38912
	ds_read_b128 v[222:225], v203 offset:39936
	global_load_lds_dwordx4 v[198:199], off
	v_lshl_add_u64 v[198:199], s[8:9], 0, v[156:157]
	s_mov_b32 m0, s68
	s_nop 0
	global_load_lds_dwordx4 v[198:199], off
	s_waitcnt vmcnt(8)
	s_waitcnt lgkmcnt(0)
	s_barrier
	v_mfma_f32_16x16x32_bf16 v[134:137], v[110:113], v[182:185], v[134:137]
	v_mfma_f32_16x16x32_bf16 v[130:133], v[138:141], v[182:185], v[130:133]
	v_mfma_f32_16x16x32_bf16 v[114:117], v[110:113], v[190:193], v[114:117]
	v_mfma_f32_16x16x32_bf16 v[106:109], v[138:141], v[190:193], v[106:109]
	v_mfma_f32_16x16x32_bf16 v[94:97], v[110:113], v[204:207], v[94:97]
	v_mfma_f32_16x16x32_bf16 v[90:93], v[138:141], v[204:207], v[90:93]
	v_mfma_f32_16x16x32_bf16 v[78:81], v[110:113], v[212:215], v[78:81]
	v_mfma_f32_16x16x32_bf16 v[74:77], v[138:141], v[212:215], v[74:77]
	v_mfma_f32_16x16x32_bf16 v[134:137], v[118:121], v[186:189], v[134:137]
	v_mfma_f32_16x16x32_bf16 v[130:133], v[142:145], v[186:189], v[130:133]
	v_mfma_f32_16x16x32_bf16 v[114:117], v[118:121], v[194:197], v[114:117]
	v_mfma_f32_16x16x32_bf16 v[106:109], v[142:145], v[194:197], v[106:109]
	v_mfma_f32_16x16x32_bf16 v[94:97], v[118:121], v[208:211], v[94:97]
	v_mfma_f32_16x16x32_bf16 v[90:93], v[142:145], v[208:211], v[90:93]
	v_mfma_f32_16x16x32_bf16 v[78:81], v[118:121], v[222:225], v[78:81]
	v_mfma_f32_16x16x32_bf16 v[74:77], v[142:145], v[222:225], v[74:77]
	v_mfma_f32_16x16x32_bf16 v[126:129], v[146:149], v[182:185], v[126:129]
	v_mfma_f32_16x16x32_bf16 v[122:125], v[174:177], v[182:185], v[122:125]
	v_mfma_f32_16x16x32_bf16 v[102:105], v[146:149], v[190:193], v[102:105]
	v_mfma_f32_16x16x32_bf16 v[98:101], v[174:177], v[190:193], v[98:101]
	v_mfma_f32_16x16x32_bf16 v[86:89], v[146:149], v[204:207], v[86:89]
	v_mfma_f32_16x16x32_bf16 v[82:85], v[174:177], v[204:207], v[82:85]
	v_mfma_f32_16x16x32_bf16 v[70:73], v[146:149], v[212:215], v[70:73]
	v_mfma_f32_16x16x32_bf16 v[66:69], v[174:177], v[212:215], v[66:69]
	v_mfma_f32_16x16x32_bf16 v[126:129], v[150:153], v[186:189], v[126:129]
	v_mfma_f32_16x16x32_bf16 v[122:125], v[178:181], v[186:189], v[122:125]
	v_mfma_f32_16x16x32_bf16 v[102:105], v[150:153], v[194:197], v[102:105]
	v_mfma_f32_16x16x32_bf16 v[98:101], v[178:181], v[194:197], v[98:101]
	v_mfma_f32_16x16x32_bf16 v[86:89], v[150:153], v[208:211], v[86:89]
	v_mfma_f32_16x16x32_bf16 v[82:85], v[178:181], v[208:211], v[82:85]
	v_mfma_f32_16x16x32_bf16 v[70:73], v[150:153], v[222:225], v[70:73]
	v_mfma_f32_16x16x32_bf16 v[66:69], v[178:181], v[222:225], v[66:69]
	s_barrier
	s_add_i32 s8, s36, s64
	v_lshl_add_u64 v[168:169], v[168:169], 0, s[44:45]
	s_mov_b32 m0, s8
	ds_read_b128 v[182:185], v203 offset:49152
	ds_read_b128 v[186:189], v203 offset:50176
	ds_read_b128 v[190:193], v203 offset:51200
	ds_read_b128 v[194:197], v203 offset:52224
	ds_read_b128 v[204:207], v203 offset:53248
	ds_read_b128 v[208:211], v203 offset:54272
	ds_read_b128 v[212:215], v203 offset:55296
	ds_read_b128 v[222:225], v203 offset:56320
	global_load_lds_dwordx4 v[168:169], off
	s_add_i32 m0, s8, 0x2000
	s_add_u32 s8, s58, 0x160080
	v_lshl_add_u64 v[168:169], v[170:171], 0, s[44:45]
	s_addc_u32 s9, s59, 0
	s_add_i32 s36, s37, s64
	global_load_lds_dwordx4 v[168:169], off
	v_lshl_add_u64 v[168:169], s[8:9], 0, v[162:163]
	s_mov_b32 m0, s36
	s_nop 0
	global_load_lds_dwordx4 v[168:169], off
	v_lshl_add_u64 v[168:169], s[8:9], 0, v[158:159]
	s_add_i32 m0, s36, 0x2000
	s_nop 0
	global_load_lds_dwordx4 v[168:169], off
	v_lshl_add_u64 v[168:169], s[56:57], 0, v[154:155]
	s_mov_b32 m0, s69
	s_nop 0
	global_load_lds_dwordx4 v[168:169], off
	v_lshl_add_u64 v[168:169], s[56:57], 0, v[156:157]
	s_mov_b32 m0, s70
	s_nop 0
	global_load_lds_dwordx4 v[168:169], off
	s_waitcnt vmcnt(8)
	s_waitcnt lgkmcnt(0)
	s_barrier
	v_mfma_f32_16x16x32_bf16 v[62:65], v[110:113], v[182:185], v[62:65]
	v_mfma_f32_16x16x32_bf16 v[58:61], v[138:141], v[182:185], v[58:61]
	v_mfma_f32_16x16x32_bf16 v[46:49], v[110:113], v[190:193], v[46:49]
	v_mfma_f32_16x16x32_bf16 v[42:45], v[138:141], v[190:193], v[42:45]
	v_mfma_f32_16x16x32_bf16 v[30:33], v[110:113], v[204:207], v[30:33]
	v_mfma_f32_16x16x32_bf16 v[26:29], v[138:141], v[204:207], v[26:29]
	v_mfma_f32_16x16x32_bf16 v[14:17], v[110:113], v[212:215], v[14:17]
	v_mfma_f32_16x16x32_bf16 v[10:13], v[138:141], v[212:215], v[10:13]
	v_mfma_f32_16x16x32_bf16 v[62:65], v[118:121], v[186:189], v[62:65]
	v_mfma_f32_16x16x32_bf16 v[58:61], v[142:145], v[186:189], v[58:61]
	v_mfma_f32_16x16x32_bf16 v[46:49], v[118:121], v[194:197], v[46:49]
	v_mfma_f32_16x16x32_bf16 v[42:45], v[142:145], v[194:197], v[42:45]
	v_mfma_f32_16x16x32_bf16 v[30:33], v[118:121], v[208:211], v[30:33]
	v_mfma_f32_16x16x32_bf16 v[26:29], v[142:145], v[208:211], v[26:29]
	v_mfma_f32_16x16x32_bf16 v[14:17], v[118:121], v[222:225], v[14:17]
	v_mfma_f32_16x16x32_bf16 v[10:13], v[142:145], v[222:225], v[10:13]
	v_mfma_f32_16x16x32_bf16 v[54:57], v[146:149], v[182:185], v[54:57]
	v_mfma_f32_16x16x32_bf16 v[50:53], v[174:177], v[182:185], v[50:53]
	v_mfma_f32_16x16x32_bf16 v[38:41], v[146:149], v[190:193], v[38:41]
	v_mfma_f32_16x16x32_bf16 v[34:37], v[174:177], v[190:193], v[34:37]
	v_mfma_f32_16x16x32_bf16 v[22:25], v[146:149], v[204:207], v[22:25]
	v_mfma_f32_16x16x32_bf16 v[18:21], v[174:177], v[204:207], v[18:21]
	v_mfma_f32_16x16x32_bf16 v[6:9], v[146:149], v[212:215], v[6:9]
	v_mfma_f32_16x16x32_bf16 v[2:5], v[174:177], v[212:215], v[2:5]
	v_mfma_f32_16x16x32_bf16 v[54:57], v[150:153], v[186:189], v[54:57]
	v_mfma_f32_16x16x32_bf16 v[50:53], v[178:181], v[186:189], v[50:53]
	v_mfma_f32_16x16x32_bf16 v[38:41], v[150:153], v[194:197], v[38:41]
	v_mfma_f32_16x16x32_bf16 v[34:37], v[178:181], v[194:197], v[34:37]
	v_mfma_f32_16x16x32_bf16 v[22:25], v[150:153], v[208:211], v[22:25]
	v_mfma_f32_16x16x32_bf16 v[18:21], v[178:181], v[208:211], v[18:21]
	v_mfma_f32_16x16x32_bf16 v[6:9], v[150:153], v[222:225], v[6:9]
	v_mfma_f32_16x16x32_bf16 v[2:5], v[178:181], v[222:225], v[2:5]
	s_barrier
	s_add_i32 s84, s84, 2
	s_add_u32 s26, s26, 0x10000
	s_addc_u32 s27, s27, 0
	s_add_u32 s82, s82, 0x100
	s_addc_u32 s83, s83, 0
	s_cmpk_gt_u32 s84, 0x55
	s_cbranch_scc0 .LBB0_1446
	s_and_b64 vcc, exec, s[20:21]
	s_cbranch_vccz .LBB0_1449
	s_barrier

.LBB0_1465:
	s_or_b64 exec, exec, s[26:27]
	s_and_b64 vcc, exec, s[6:7]
	s_mov_b64 s[6:7], -1
	s_cbranch_vccnz .LBB0_1432
	s_mov_b32 s101, 1
	s_andn2_b64 vcc, exec, s[10:11]
	s_cbranch_vccnz .LBB0_1431
	s_barrier
	s_branch .LBB0_1431

.LBB0_1598:
	s_mov_b32 s101, 0
	s_add_u32 s14, s6, 0x44000000
	s_addc_u32 s15, s7, 0
	v_readlane_b32 s20, v255, 23
	s_add_u32 s16, s6, 0x63000000
	v_readlane_b32 s21, v255, 24
	s_addc_u32 s17, s7, 0
	s_lshl_b64 s[20:21], s[20:21], 3
	s_add_u32 s5, s5, s20
	s_addc_u32 s19, s18, s21
	s_add_u32 s18, s5, 0x80000
	s_addc_u32 s19, s19, 0
	s_add_u32 s20, s6, 0x69000000
	v_bfe_u32 v17, v195, 4, 2
	s_addc_u32 s21, s7, 0
	v_and_b32_e32 v16, 15, v195
	v_lshlrev_b32_e32 v18, 4, v17
	s_lshl_b32 s4, s4, 5
	v_lshl_or_b32 v197, s23, 6, v16
	v_lshl_or_b32 v16, v16, 6, v18
	v_lshlrev_b32_e32 v18, 2, v195
	s_and_b32 s81, s4, 0x60
	s_add_i32 m0, s63, 0x18000
	v_lshl_add_u64 v[8:9], v[8:9], 0, s[44:45]
	s_lshl_b32 s5, s23, 13
	v_and_b32_e32 v18, 32, v18
	s_lshl_b32 s4, s81, 7
	s_waitcnt vmcnt(2)
	s_barrier
	global_load_lds_dwordx4 v[8:9], off
	v_lshl_add_u64 v[6:7], v[6:7], 0, s[44:45]
	s_add_i32 m0, s63, 0x1a000
	s_add_i32 s82, s63, 0x8000
	s_add_i32 s83, s63, 0xa000
	v_bitop3_b32 v201, v16, s4, v18 bitop3:0xde
	global_load_lds_dwordx4 v[6:7], off
	v_lshl_add_u64 v[2:3], v[2:3], 0, s[44:45]
	s_mov_b32 m0, s82
	s_add_u32 s4, s66, 0x90080
	v_bitop3_b32 v19, v16, s5, v18 bitop3:0xde
	global_load_lds_dwordx4 v[2:3], off
	v_lshl_add_u64 v[2:3], v[4:5], 0, s[44:45]
	s_mov_b32 m0, s83
	s_addc_u32 s5, s67, 0
	global_load_lds_dwordx4 v[2:3], off
	s_add_i32 m0, s63, 0x1c000
	v_lshl_add_u64 v[2:3], s[4:5], 0, v[162:163]
	global_load_lds_dwordx4 v[2:3], off
	v_lshl_add_u64 v[2:3], s[4:5], 0, v[176:177]
	s_add_i32 m0, s63, 0x1e000
	s_and_b32 s85, s2, 7
	global_load_lds_dwordx4 v[2:3], off
	v_lshlrev_b32_e32 v2, 14, v13
	v_and_b32_e32 v2, 0xffff8000, v2
	v_lshl_add_u32 v2, v14, 11, v2
	v_and_b32_e32 v3, 1, v13
	v_lshl_or_b32 v2, v3, 6, v2
	s_ashr_i32 s86, s2, 3
	v_lshl_add_u32 v178, v15, 1, v2
	v_lshlrev_b32_e32 v2, 14, v10
	s_lshl_b32 s4, s85, 3
	s_and_b32 s5, s86, 7
	v_and_b32_e32 v2, 0xffff8000, v2
	s_waitcnt vmcnt(6)
	s_ashr_i32 s84, s2, 31
	s_or_b32 s87, s4, s5
	v_lshl_add_u32 v2, v11, 11, v2
	v_and_b32_e32 v3, 1, v10
	v_lshlrev_b32_e32 v199, 3, v17
	s_cmpk_lt_u32 s22, 0x100
	v_lshl_or_b32 v2, v3, 6, v2
	s_cselect_b64 s[22:23], -1, 0
	v_lshlrev_b32_e32 v216, 3, v197
	s_mov_b32 s89, 0
	v_cmp_eq_u32_e64 s[4:5], 0, v17
	v_or_b32_e32 v217, s81, v199
	v_mov_b32_e32 v179, v163
	v_lshl_add_u32 v180, v12, 1, v2
	v_mov_b32_e32 v181, v163
	v_add_u32_e32 v222, 0, v19
	s_mov_b32 s88, 0
	s_barrier
	s_branch .LBB0_1601

.LBB0_1615:
	s_add_u32 s31, s64, 0xfffc0080
	s_addc_u32 s36, s65, -1
	s_add_i32 s37, 0, 0x10000
	s_cmp_eq_u32 s27, 12
	s_cselect_b32 vcc_hi, s57, s36
	s_cselect_b32 vcc_lo, s56, s31
	s_cselect_b32 s67, s59, s26
	s_cselect_b32 s66, s58, s25
	s_add_i32 s31, 0, 0x14000
	v_add_u32_e32 v142, s37, v201
	v_add_u32_e32 v158, s31, v201
	ds_read_b128 v[66:69], v142
	ds_read_b128 v[70:73], v142 offset:1024
	ds_read_b128 v[138:141], v142 offset:2048
	ds_read_b128 v[142:145], v142 offset:3072
	ds_read_b128 v[146:149], v158
	ds_read_b128 v[150:153], v158 offset:1024
	ds_read_b128 v[154:157], v158 offset:2048
	ds_read_b128 v[158:161], v158 offset:3072
	v_lshl_add_u64 v[168:169], s[64:65], 0, v[180:181]
	s_add_i32 m0, s63, 0xc000
	ds_read_b128 v[182:185], v222
	ds_read_b128 v[186:189], v222 offset:1024
	ds_read_b128 v[190:193], v222 offset:2048
	ds_read_b128 v[202:205], v222 offset:3072
	ds_read_b128 v[206:209], v222 offset:4096
	ds_read_b128 v[210:213], v222 offset:5120
	ds_read_b128 v[224:227], v222 offset:6144
	ds_read_b128 v[228:231], v222 offset:7168
	global_load_lds_dwordx4 v[168:169], off
	v_lshl_add_u64 v[168:169], s[64:65], 0, v[178:179]
	s_add_i32 m0, s63, 0xe000
	s_nop 0
	global_load_lds_dwordx4 v[168:169], off
	s_waitcnt vmcnt(63)
	s_cmp_eq_i32 s27, -2
	s_cselect_b32 s100, s101, 0
	s_cmp_lg_u32 s100, 0
	s_cbranch_scc1 .Lrw_skip1615_0
	s_waitcnt vmcnt(8)
.Lrw_skip1615_0:
	s_waitcnt lgkmcnt(0)
	s_barrier
	v_mfma_i32_16x16x64_i8 v[134:137], v[66:69], v[182:185], v[134:137]
	v_mfma_i32_16x16x64_i8 v[130:133], v[138:141], v[182:185], v[130:133]
	v_mfma_i32_16x16x64_i8 v[126:129], v[66:69], v[190:193], v[126:129]
	v_mfma_i32_16x16x64_i8 v[122:125], v[138:141], v[190:193], v[122:125]
	v_mfma_i32_16x16x64_i8 v[118:121], v[66:69], v[206:209], v[118:121]
	v_mfma_i32_16x16x64_i8 v[114:117], v[138:141], v[206:209], v[114:117]
	v_mfma_i32_16x16x64_i8 v[78:81], v[66:69], v[224:227], v[78:81]
	v_mfma_i32_16x16x64_i8 v[74:77], v[138:141], v[224:227], v[74:77]
	v_mfma_i32_16x16x64_i8 v[134:137], v[70:73], v[186:189], v[134:137]
	v_mfma_i32_16x16x64_i8 v[130:133], v[142:145], v[186:189], v[130:133]
	v_mfma_i32_16x16x64_i8 v[126:129], v[70:73], v[202:205], v[126:129]
	v_mfma_i32_16x16x64_i8 v[122:125], v[142:145], v[202:205], v[122:125]
	v_mfma_i32_16x16x64_i8 v[118:121], v[70:73], v[210:213], v[118:121]
	v_mfma_i32_16x16x64_i8 v[114:117], v[142:145], v[210:213], v[114:117]
	v_mfma_i32_16x16x64_i8 v[78:81], v[70:73], v[228:231], v[78:81]
	v_mfma_i32_16x16x64_i8 v[74:77], v[142:145], v[228:231], v[74:77]
	v_mfma_i32_16x16x64_i8 v[110:113], v[146:149], v[182:185], v[110:113]
	v_mfma_i32_16x16x64_i8 v[106:109], v[154:157], v[182:185], v[106:109]
	v_mfma_i32_16x16x64_i8 v[102:105], v[146:149], v[190:193], v[102:105]
	v_mfma_i32_16x16x64_i8 v[98:101], v[154:157], v[190:193], v[98:101]
	v_mfma_i32_16x16x64_i8 v[94:97], v[146:149], v[206:209], v[94:97]
	v_mfma_i32_16x16x64_i8 v[90:93], v[154:157], v[206:209], v[90:93]
	v_mfma_i32_16x16x64_i8 v[86:89], v[146:149], v[224:227], v[86:89]
	v_mfma_i32_16x16x64_i8 v[82:85], v[154:157], v[224:227], v[82:85]
	v_mfma_i32_16x16x64_i8 v[110:113], v[150:153], v[186:189], v[110:113]
	v_mfma_i32_16x16x64_i8 v[106:109], v[158:161], v[186:189], v[106:109]
	v_mfma_i32_16x16x64_i8 v[102:105], v[150:153], v[202:205], v[102:105]
	v_mfma_i32_16x16x64_i8 v[98:101], v[158:161], v[202:205], v[98:101]
	v_mfma_i32_16x16x64_i8 v[94:97], v[150:153], v[210:213], v[94:97]
	v_mfma_i32_16x16x64_i8 v[90:93], v[158:161], v[210:213], v[90:93]
	v_mfma_i32_16x16x64_i8 v[86:89], v[150:153], v[228:231], v[86:89]
	v_mfma_i32_16x16x64_i8 v[82:85], v[158:161], v[228:231], v[82:85]
	s_barrier
	s_add_i32 s36, s37, s61
	v_lshl_add_u64 v[168:169], s[66:67], 0, v[162:163]
	s_mov_b32 m0, s36
	ds_read_b128 v[182:185], v222 offset:16384
	ds_read_b128 v[186:189], v222 offset:17408
	ds_read_b128 v[190:193], v222 offset:18432
	ds_read_b128 v[202:205], v222 offset:19456
	ds_read_b128 v[206:209], v222 offset:20480
	ds_read_b128 v[210:213], v222 offset:21504
	ds_read_b128 v[224:227], v222 offset:22528
	ds_read_b128 v[228:231], v222 offset:23552
	global_load_lds_dwordx4 v[168:169], off
	s_add_i32 m0, s36, 0x2000
	s_add_u32 s36, s66, 0x90000
	v_lshl_add_u64 v[170:171], s[66:67], 0, v[176:177]
	s_addc_u32 s37, s67, 0
	s_add_i32 s31, s31, s61
	global_load_lds_dwordx4 v[170:171], off
	v_lshl_add_u64 v[214:215], s[36:37], 0, v[162:163]
	s_mov_b32 m0, s31
	v_lshl_add_u64 v[232:233], vcc, 0, v[174:175]
	global_load_lds_dwordx4 v[214:215], off
	v_lshl_add_u64 v[214:215], s[36:37], 0, v[176:177]
	s_add_i32 m0, s31, 0x2000
	s_nop 0
	global_load_lds_dwordx4 v[214:215], off
	v_lshl_add_u64 v[214:215], vcc, 0, v[172:173]
	s_mov_b32 m0, s63
	s_nop 0
	global_load_lds_dwordx4 v[214:215], off
	s_mov_b32 m0, s78
	s_nop 0
	global_load_lds_dwordx4 v[232:233], off
	s_waitcnt vmcnt(63)
	s_cmp_eq_i32 s27, -2
	s_cselect_b32 s100, s101, 0
	s_cmp_lg_u32 s100, 0
	s_cbranch_scc1 .Lrw_skip1615_1
	s_waitcnt vmcnt(8)
.Lrw_skip1615_1:
	s_waitcnt lgkmcnt(0)
	s_barrier
	v_mfma_i32_16x16x64_i8 v[62:65], v[66:69], v[182:185], v[62:65]
	v_mfma_i32_16x16x64_i8 v[58:61], v[138:141], v[182:185], v[58:61]
	v_mfma_i32_16x16x64_i8 v[54:57], v[66:69], v[190:193], v[54:57]
	v_mfma_i32_16x16x64_i8 v[50:53], v[138:141], v[190:193], v[50:53]
	v_mfma_i32_16x16x64_i8 v[46:49], v[66:69], v[206:209], v[46:49]
	v_mfma_i32_16x16x64_i8 v[42:45], v[138:141], v[206:209], v[42:45]
	v_mfma_i32_16x16x64_i8 v[38:41], v[66:69], v[224:227], v[38:41]
	v_mfma_i32_16x16x64_i8 v[34:37], v[138:141], v[224:227], v[34:37]
	v_mfma_i32_16x16x64_i8 v[62:65], v[70:73], v[186:189], v[62:65]
	v_mfma_i32_16x16x64_i8 v[58:61], v[142:145], v[186:189], v[58:61]
	v_mfma_i32_16x16x64_i8 v[54:57], v[70:73], v[202:205], v[54:57]
	v_mfma_i32_16x16x64_i8 v[50:53], v[142:145], v[202:205], v[50:53]
	v_mfma_i32_16x16x64_i8 v[46:49], v[70:73], v[210:213], v[46:49]
	v_mfma_i32_16x16x64_i8 v[42:45], v[142:145], v[210:213], v[42:45]
	v_mfma_i32_16x16x64_i8 v[38:41], v[70:73], v[228:231], v[38:41]
	v_mfma_i32_16x16x64_i8 v[34:37], v[142:145], v[228:231], v[34:37]
	v_mfma_i32_16x16x64_i8 v[30:33], v[146:149], v[182:185], v[30:33]
	v_mfma_i32_16x16x64_i8 v[26:29], v[154:157], v[182:185], v[26:29]
	v_mfma_i32_16x16x64_i8 v[22:25], v[146:149], v[190:193], v[22:25]
	v_mfma_i32_16x16x64_i8 v[18:21], v[154:157], v[190:193], v[18:21]
	v_mfma_i32_16x16x64_i8 v[14:17], v[146:149], v[206:209], v[14:17]
	v_mfma_i32_16x16x64_i8 v[10:13], v[154:157], v[206:209], v[10:13]
	v_mfma_i32_16x16x64_i8 v[6:9], v[146:149], v[224:227], v[6:9]
	v_mfma_i32_16x16x64_i8 v[2:5], v[154:157], v[224:227], v[2:5]
	v_mfma_i32_16x16x64_i8 v[30:33], v[150:153], v[186:189], v[30:33]
	v_mfma_i32_16x16x64_i8 v[26:29], v[158:161], v[186:189], v[26:29]
	v_mfma_i32_16x16x64_i8 v[22:25], v[150:153], v[202:205], v[22:25]
	v_mfma_i32_16x16x64_i8 v[18:21], v[158:161], v[202:205], v[18:21]
	v_mfma_i32_16x16x64_i8 v[14:17], v[150:153], v[210:213], v[14:17]
	v_mfma_i32_16x16x64_i8 v[10:13], v[158:161], v[210:213], v[10:13]
	v_mfma_i32_16x16x64_i8 v[6:9], v[150:153], v[228:231], v[6:9]
	v_mfma_i32_16x16x64_i8 v[2:5], v[158:161], v[228:231], v[2:5]
	s_barrier
	s_add_i32 s31, 0, 0x18000
	s_add_i32 s38, 0, 0x1c000
	v_add_u32_e32 v142, s31, v201
	v_add_u32_e32 v158, s38, v201
	ds_read_b128 v[66:69], v142
	ds_read_b128 v[70:73], v142 offset:1024
	ds_read_b128 v[138:141], v142 offset:2048
	ds_read_b128 v[142:145], v142 offset:3072
	ds_read_b128 v[146:149], v158
	ds_read_b128 v[150:153], v158 offset:1024
	ds_read_b128 v[154:157], v158 offset:2048
	ds_read_b128 v[158:161], v158 offset:3072
	s_add_u32 s36, vcc_lo, 0x40000
	s_addc_u32 s37, vcc_hi, 0
	s_mov_b32 m0, s79
	v_lshl_add_u64 v[234:235], s[36:37], 0, v[172:173]
	ds_read_b128 v[182:185], v222 offset:32768
	ds_read_b128 v[186:189], v222 offset:33792
	ds_read_b128 v[190:193], v222 offset:34816
	ds_read_b128 v[202:205], v222 offset:35840
	ds_read_b128 v[206:209], v222 offset:36864
	ds_read_b128 v[210:213], v222 offset:37888
	ds_read_b128 v[224:227], v222 offset:38912
	ds_read_b128 v[228:231], v222 offset:39936
	global_load_lds_dwordx4 v[234:235], off
	v_lshl_add_u64 v[234:235], s[36:37], 0, v[174:175]
	s_mov_b32 m0, s80
	s_nop 0
	global_load_lds_dwordx4 v[234:235], off
	s_waitcnt vmcnt(8)
	s_waitcnt lgkmcnt(0)
	s_barrier
	v_mfma_i32_16x16x64_i8 v[134:137], v[66:69], v[182:185], v[134:137]
	v_mfma_i32_16x16x64_i8 v[130:133], v[138:141], v[182:185], v[130:133]
	v_mfma_i32_16x16x64_i8 v[126:129], v[66:69], v[190:193], v[126:129]
	v_mfma_i32_16x16x64_i8 v[122:125], v[138:141], v[190:193], v[122:125]
	v_mfma_i32_16x16x64_i8 v[118:121], v[66:69], v[206:209], v[118:121]
	v_mfma_i32_16x16x64_i8 v[114:117], v[138:141], v[206:209], v[114:117]
	v_mfma_i32_16x16x64_i8 v[78:81], v[66:69], v[224:227], v[78:81]
	v_mfma_i32_16x16x64_i8 v[74:77], v[138:141], v[224:227], v[74:77]
	v_mfma_i32_16x16x64_i8 v[134:137], v[70:73], v[186:189], v[134:137]
	v_mfma_i32_16x16x64_i8 v[130:133], v[142:145], v[186:189], v[130:133]
	v_mfma_i32_16x16x64_i8 v[126:129], v[70:73], v[202:205], v[126:129]
	v_mfma_i32_16x16x64_i8 v[122:125], v[142:145], v[202:205], v[122:125]
	v_mfma_i32_16x16x64_i8 v[118:121], v[70:73], v[210:213], v[118:121]
	v_mfma_i32_16x16x64_i8 v[114:117], v[142:145], v[210:213], v[114:117]
	v_mfma_i32_16x16x64_i8 v[78:81], v[70:73], v[228:231], v[78:81]
	v_mfma_i32_16x16x64_i8 v[74:77], v[142:145], v[228:231], v[74:77]
	v_mfma_i32_16x16x64_i8 v[110:113], v[146:149], v[182:185], v[110:113]
	v_mfma_i32_16x16x64_i8 v[106:109], v[154:157], v[182:185], v[106:109]
	v_mfma_i32_16x16x64_i8 v[102:105], v[146:149], v[190:193], v[102:105]
	v_mfma_i32_16x16x64_i8 v[98:101], v[154:157], v[190:193], v[98:101]
	v_mfma_i32_16x16x64_i8 v[94:97], v[146:149], v[206:209], v[94:97]
	v_mfma_i32_16x16x64_i8 v[90:93], v[154:157], v[206:209], v[90:93]
	v_mfma_i32_16x16x64_i8 v[86:89], v[146:149], v[224:227], v[86:89]
	v_mfma_i32_16x16x64_i8 v[82:85], v[154:157], v[224:227], v[82:85]
	v_mfma_i32_16x16x64_i8 v[110:113], v[150:153], v[186:189], v[110:113]
	v_mfma_i32_16x16x64_i8 v[106:109], v[158:161], v[186:189], v[106:109]
	v_mfma_i32_16x16x64_i8 v[102:105], v[150:153], v[202:205], v[102:105]
	v_mfma_i32_16x16x64_i8 v[98:101], v[158:161], v[202:205], v[98:101]
	v_mfma_i32_16x16x64_i8 v[94:97], v[150:153], v[210:213], v[94:97]
	v_mfma_i32_16x16x64_i8 v[90:93], v[158:161], v[210:213], v[90:93]
	v_mfma_i32_16x16x64_i8 v[86:89], v[150:153], v[228:231], v[86:89]
	v_mfma_i32_16x16x64_i8 v[82:85], v[158:161], v[228:231], v[82:85]
	s_barrier
	s_add_i32 s31, s31, s61
	v_lshl_add_u64 v[168:169], v[168:169], 0, s[44:45]
	s_mov_b32 m0, s31
	ds_read_b128 v[182:185], v222 offset:49152
	ds_read_b128 v[186:189], v222 offset:50176
	ds_read_b128 v[190:193], v222 offset:51200
	ds_read_b128 v[202:205], v222 offset:52224
	ds_read_b128 v[206:209], v222 offset:53248
	ds_read_b128 v[210:213], v222 offset:54272
	ds_read_b128 v[224:227], v222 offset:55296
	ds_read_b128 v[228:231], v222 offset:56320
	global_load_lds_dwordx4 v[168:169], off
	s_add_i32 m0, s31, 0x2000
	s_add_u32 s36, s66, 0x90080
	v_lshl_add_u64 v[168:169], v[170:171], 0, s[44:45]
	s_addc_u32 s37, s67, 0
	s_add_i32 s31, s38, s61
	global_load_lds_dwordx4 v[168:169], off
	v_lshl_add_u64 v[168:169], s[36:37], 0, v[162:163]
	s_mov_b32 m0, s31
	s_nop 0
	global_load_lds_dwordx4 v[168:169], off
	v_lshl_add_u64 v[168:169], s[36:37], 0, v[176:177]
	s_add_i32 m0, s31, 0x2000
	s_nop 0
	global_load_lds_dwordx4 v[168:169], off
	v_lshl_add_u64 v[168:169], v[214:215], 0, s[44:45]
	s_mov_b32 m0, s82
	s_nop 0
	global_load_lds_dwordx4 v[168:169], off
	v_lshl_add_u64 v[168:169], v[232:233], 0, s[44:45]
	s_mov_b32 m0, s83
	s_nop 0
	global_load_lds_dwordx4 v[168:169], off
	s_waitcnt vmcnt(8)
	s_waitcnt lgkmcnt(0)
	s_barrier
	v_mfma_i32_16x16x64_i8 v[62:65], v[66:69], v[182:185], v[62:65]
	v_mfma_i32_16x16x64_i8 v[58:61], v[138:141], v[182:185], v[58:61]
	v_mfma_i32_16x16x64_i8 v[54:57], v[66:69], v[190:193], v[54:57]
	v_mfma_i32_16x16x64_i8 v[50:53], v[138:141], v[190:193], v[50:53]
	v_mfma_i32_16x16x64_i8 v[46:49], v[66:69], v[206:209], v[46:49]
	v_mfma_i32_16x16x64_i8 v[42:45], v[138:141], v[206:209], v[42:45]
	v_mfma_i32_16x16x64_i8 v[38:41], v[66:69], v[224:227], v[38:41]
	v_mfma_i32_16x16x64_i8 v[34:37], v[138:141], v[224:227], v[34:37]
	v_mfma_i32_16x16x64_i8 v[62:65], v[70:73], v[186:189], v[62:65]
	v_mfma_i32_16x16x64_i8 v[58:61], v[142:145], v[186:189], v[58:61]
	v_mfma_i32_16x16x64_i8 v[54:57], v[70:73], v[202:205], v[54:57]
	v_mfma_i32_16x16x64_i8 v[50:53], v[142:145], v[202:205], v[50:53]
	v_mfma_i32_16x16x64_i8 v[46:49], v[70:73], v[210:213], v[46:49]
	v_mfma_i32_16x16x64_i8 v[42:45], v[142:145], v[210:213], v[42:45]
	v_mfma_i32_16x16x64_i8 v[38:41], v[70:73], v[228:231], v[38:41]
	v_mfma_i32_16x16x64_i8 v[34:37], v[142:145], v[228:231], v[34:37]
	v_mfma_i32_16x16x64_i8 v[30:33], v[146:149], v[182:185], v[30:33]
	v_mfma_i32_16x16x64_i8 v[26:29], v[154:157], v[182:185], v[26:29]
	v_mfma_i32_16x16x64_i8 v[22:25], v[146:149], v[190:193], v[22:25]
	v_mfma_i32_16x16x64_i8 v[18:21], v[154:157], v[190:193], v[18:21]
	v_mfma_i32_16x16x64_i8 v[14:17], v[146:149], v[206:209], v[14:17]
	v_mfma_i32_16x16x64_i8 v[10:13], v[154:157], v[206:209], v[10:13]
	v_mfma_i32_16x16x64_i8 v[6:9], v[146:149], v[224:227], v[6:9]
	v_mfma_i32_16x16x64_i8 v[2:5], v[154:157], v[224:227], v[2:5]
	v_mfma_i32_16x16x64_i8 v[30:33], v[150:153], v[186:189], v[30:33]
	v_mfma_i32_16x16x64_i8 v[26:29], v[158:161], v[186:189], v[26:29]
	v_mfma_i32_16x16x64_i8 v[22:25], v[150:153], v[202:205], v[22:25]
	v_mfma_i32_16x16x64_i8 v[18:21], v[158:161], v[202:205], v[18:21]
	v_mfma_i32_16x16x64_i8 v[14:17], v[150:153], v[210:213], v[14:17]
	v_mfma_i32_16x16x64_i8 v[10:13], v[158:161], v[210:213], v[10:13]
	v_mfma_i32_16x16x64_i8 v[6:9], v[150:153], v[228:231], v[6:9]
	v_mfma_i32_16x16x64_i8 v[2:5], v[158:161], v[228:231], v[2:5]
	s_barrier
	s_add_i32 s27, s27, 2
	s_add_u32 s25, s25, 0x100
	s_addc_u32 s26, s26, 0
	s_add_u32 s64, s64, 0x100
	s_addc_u32 s65, s65, 0
	s_cmp_gt_u32 s27, 13
	s_cbranch_scc0 .LBB0_1615
	s_and_b64 vcc, exec, s[22:23]
	s_cbranch_vccz .LBB0_1618
	s_barrier

.LBB0_1637:
	s_mov_b32 s101, 1
	s_andn2_b64 vcc, exec, s[12:13]
	s_cbranch_vccnz .LBB0_1599
	s_barrier
	s_branch .LBB0_1599
